# GEMM main loops: s_setprio toggling removed (8 per iteration; a priority-swap run showed no sensitivity)
# speedup vs baseline: 1.0081x; 1.0081x over previous
; #define PG8_STAGE(bufoff, gbase, voff) do { _Pragma("unroll") for (int _i = 0; _i < 2; ++_i) \
;         __builtin_amdgcn_global_load_lds((const unsigned*)((const char*)(gbase) + (voff)[_i]), (LAS unsigned*)(lds + (bufoff) + ldsw + _i * 8192), 16, 0, 0); } while (0)
; #define PG8_LDA(dst, b, h) do { _Pragma("unroll") for (int m = 0; m < 4; ++m) _Pragma("unroll") for (int k = 0; k < 2; ++k) dst[m][k] = *(const LAS bf16x8*)(lds + PG8_SA(b, h) + aoff + m * 2048 + k * 1024); } while (0)
; #define PG8_LDB(dst, b, h) do { _Pragma("unroll") for (int n = 0; n < 2; ++n) _Pragma("unroll") for (int k = 0; k < 2; ++k) dst[n][k] = *(const LAS bf16x8*)(lds + PG8_SB(b, h) + boff + n * 2048 + k * 1024); } while (0)
; #define PG8_MMA(ai, bj, At, Bt) do { __builtin_amdgcn_s_setprio(1); _Pragma("unroll") for (int m = 0; m < 4; ++m) _Pragma("unroll") for (int n = 0; n < 2; ++n) _Pragma("unroll") for (int k = 0; k < 2; ++k) \
;         acc[ai][bj][m][n] = __builtin_amdgcn_mfma_f32_16x16x32_bf16(Bt[n][k], At[m][k], acc[ai][bj][m][n], 0, 0, 0); __builtin_amdgcn_s_setprio(0); } while (0)
; #define PG8_WAIT_V(n) asm volatile("s_waitcnt vmcnt(" #n ")" ::: "memory")
; #define PG8_WAIT_L(n) asm volatile("s_waitcnt lgkmcnt(" #n ")" ::: "memory")
; #define PG8_BAR __builtin_amdgcn_s_barrier()
; #define PG8_SCHED __builtin_amdgcn_sched_barrier(0)
; template <class Epi, class Sched, bool ALIGN_EPI>
; DI void gemm_phase(LAS unsigned char* lds, const Gemm g, const Sched& S, const Epi& E) {
;     ...
;             const bool last = (t == nt - 2);
;             const char* a1 = cA + (size_t)(t + 1) * kstep;
;             const char* a2 = last ? nA : cA + (size_t)(t + 2) * kstep; const char* b2 = last ? nB : cB + (size_t)(t + 2) * kstep;
;             const char* a3 = a2 + kstep; const char* b3 = b2 + kstep;
;             PG8_LDB(B0, 0, 0); PG8_LDB(B1, 0, 1); PG8_SCHED; PG8_LDA(At, 0, 0); PG8_STAGE(PG8_SA(1, 1), a1 + hstep, voffA);
;             PG8_WAIT_V(8); PG8_WAIT_L(0); PG8_BAR; PG8_MMA(0, 0, At, B0); PG8_MMA(0, 1, At, B1); PG8_BAR; PG8_SCHED;
;             PG8_LDA(At, 0, 1); PG8_STAGE(PG8_SB(0, 0), b2, voffA); PG8_STAGE(PG8_SB(0, 1), b2 + hstep, voffA); PG8_STAGE(PG8_SA(0, 0), a2, voffA);
;             PG8_WAIT_V(8); PG8_WAIT_L(0); PG8_BAR; PG8_MMA(1, 0, At, B0); PG8_MMA(1, 1, At, B1); PG8_BAR; PG8_SCHED;
.LBB0_104:
	ds_read_b128 v[48:51], v196
	ds_read_b128 v[52:55], v196 offset:1024
	ds_read_b128 v[56:59], v196 offset:2048
	ds_read_b128 v[60:63], v196 offset:3072
	ds_read_b128 v[182:185], v197
	ds_read_b128 v[186:189], v197 offset:1024
	ds_read_b128 v[200:203], v197 offset:2048
	ds_read_b128 v[204:207], v197 offset:3072
	s_add_u32 s8, s0, 0xfffc0080
	s_addc_u32 s9, s1, -1
	s_cmp_eq_u32 s47, 12
	s_cselect_b32 s45, s7, s9
	s_cselect_b32 s44, s11, s8
	s_cselect_b32 s9, s18, s46
	s_cselect_b32 s8, s29, s31
	s_add_i32 m0, s64, 0xc000
	ds_read_b128 v[208:211], v194
	ds_read_b128 v[212:215], v194 offset:1024
	ds_read_b128 v[216:219], v194 offset:2048
	ds_read_b128 v[220:223], v194 offset:3072
	ds_read_b128 v[228:231], v194 offset:4096
	ds_read_b128 v[232:235], v194 offset:5120
	ds_read_b128 v[236:239], v194 offset:6144
	ds_read_b128 v[240:243], v194 offset:7168
	global_load_lds_dwordx4 v174, s[0:1]
	s_add_i32 m0, s64, 0xe000
	s_nop 0
	global_load_lds_dwordx4 v176, s[0:1]
	s_waitcnt vmcnt(8)
	s_waitcnt lgkmcnt(0)
	s_barrier
	s_waitcnt lgkmcnt(0)
	v_mfma_f32_16x16x32_bf16 v[140:143], v[48:51], v[208:211], v[140:143]
	v_mfma_f32_16x16x32_bf16 v[136:139], v[56:59], v[208:211], v[136:139]
	v_mfma_f32_16x16x32_bf16 v[124:127], v[48:51], v[216:219], v[124:127]
	v_mfma_f32_16x16x32_bf16 v[120:123], v[56:59], v[216:219], v[120:123]
	v_mfma_f32_16x16x32_bf16 v[108:111], v[48:51], v[228:231], v[108:111]
	v_mfma_f32_16x16x32_bf16 v[104:107], v[56:59], v[228:231], v[104:107]
	v_mfma_f32_16x16x32_bf16 v[92:95], v[48:51], v[236:239], v[92:95]
	v_mfma_f32_16x16x32_bf16 v[88:91], v[56:59], v[236:239], v[88:91]
	v_mfma_f32_16x16x32_bf16 v[140:143], v[52:55], v[212:215], v[140:143]
	v_mfma_f32_16x16x32_bf16 v[136:139], v[60:63], v[212:215], v[136:139]
	v_mfma_f32_16x16x32_bf16 v[124:127], v[52:55], v[220:223], v[124:127]
	v_mfma_f32_16x16x32_bf16 v[120:123], v[60:63], v[220:223], v[120:123]
	v_mfma_f32_16x16x32_bf16 v[108:111], v[52:55], v[232:235], v[108:111]
	v_mfma_f32_16x16x32_bf16 v[104:107], v[60:63], v[232:235], v[104:107]
	v_mfma_f32_16x16x32_bf16 v[92:95], v[52:55], v[240:243], v[92:95]
	v_mfma_f32_16x16x32_bf16 v[88:91], v[60:63], v[240:243], v[88:91]
	v_mfma_f32_16x16x32_bf16 v[132:135], v[182:185], v[208:211], v[132:135]
	v_mfma_f32_16x16x32_bf16 v[128:131], v[200:203], v[208:211], v[128:131]
	v_mfma_f32_16x16x32_bf16 v[116:119], v[182:185], v[216:219], v[116:119]
	v_mfma_f32_16x16x32_bf16 v[112:115], v[200:203], v[216:219], v[112:115]
	v_mfma_f32_16x16x32_bf16 v[100:103], v[182:185], v[228:231], v[100:103]
	v_mfma_f32_16x16x32_bf16 v[96:99], v[200:203], v[228:231], v[96:99]
	v_mfma_f32_16x16x32_bf16 v[84:87], v[182:185], v[236:239], v[84:87]
	v_mfma_f32_16x16x32_bf16 v[80:83], v[200:203], v[236:239], v[80:83]
	v_mfma_f32_16x16x32_bf16 v[132:135], v[186:189], v[212:215], v[132:135]
	v_mfma_f32_16x16x32_bf16 v[128:131], v[204:207], v[212:215], v[128:131]
	v_mfma_f32_16x16x32_bf16 v[116:119], v[186:189], v[220:223], v[116:119]
	v_mfma_f32_16x16x32_bf16 v[112:115], v[204:207], v[220:223], v[112:115]
	v_mfma_f32_16x16x32_bf16 v[100:103], v[186:189], v[232:235], v[100:103]
	v_mfma_f32_16x16x32_bf16 v[96:99], v[204:207], v[232:235], v[96:99]
	v_mfma_f32_16x16x32_bf16 v[84:87], v[186:189], v[240:243], v[84:87]
	v_mfma_f32_16x16x32_bf16 v[80:83], v[204:207], v[240:243], v[80:83]
	s_barrier
	s_add_i32 s48, s75, s63
	s_add_u32 s94, s8, s22
	s_addc_u32 s95, s9, s23
	s_add_u32 s96, s44, s22
	s_addc_u32 s97, s45, s23
	s_mov_b32 m0, s48
	ds_read_b128 v[208:211], v194 offset:16384
	ds_read_b128 v[212:215], v194 offset:17408
	ds_read_b128 v[216:219], v194 offset:18432
	ds_read_b128 v[220:223], v194 offset:19456
	ds_read_b128 v[228:231], v194 offset:20480
	ds_read_b128 v[232:235], v194 offset:21504
	ds_read_b128 v[236:239], v194 offset:22528
	ds_read_b128 v[240:243], v194 offset:23552
	global_load_lds_dwordx4 v146, s[8:9]
	s_add_i32 m0, s48, 0x2000
	s_add_u32 s48, s8, 0x40000
	s_addc_u32 s49, s9, 0
	s_add_i32 s50, s76, s63
	global_load_lds_dwordx4 v148, s[8:9]
	s_mov_b32 m0, s50
	s_nop 0
	global_load_lds_dwordx4 v146, s[48:49]
	s_add_i32 m0, s50, 0x2000
	s_nop 0
	global_load_lds_dwordx4 v148, s[48:49]
	s_mov_b32 m0, s64
	s_nop 0
	global_load_lds_dwordx4 v146, s[44:45]
	s_mov_b32 m0, s65
	s_nop 0
	global_load_lds_dwordx4 v148, s[44:45]
	s_waitcnt vmcnt(8)
	s_waitcnt lgkmcnt(0)
	s_barrier
	s_waitcnt lgkmcnt(0)
	v_mfma_f32_16x16x32_bf16 v[76:79], v[48:51], v[208:211], v[76:79]
	v_mfma_f32_16x16x32_bf16 v[72:75], v[56:59], v[208:211], v[72:75]
	v_mfma_f32_16x16x32_bf16 v[44:47], v[48:51], v[216:219], v[44:47]
	v_mfma_f32_16x16x32_bf16 v[40:43], v[56:59], v[216:219], v[40:43]
	v_mfma_f32_16x16x32_bf16 v[28:31], v[48:51], v[228:231], v[28:31]
	v_mfma_f32_16x16x32_bf16 v[24:27], v[56:59], v[228:231], v[24:27]
	v_mfma_f32_16x16x32_bf16 v[12:15], v[48:51], v[236:239], v[12:15]
	v_mfma_f32_16x16x32_bf16 v[8:11], v[56:59], v[236:239], v[8:11]
	v_mfma_f32_16x16x32_bf16 v[76:79], v[52:55], v[212:215], v[76:79]
	v_mfma_f32_16x16x32_bf16 v[72:75], v[60:63], v[212:215], v[72:75]
	v_mfma_f32_16x16x32_bf16 v[44:47], v[52:55], v[220:223], v[44:47]
	v_mfma_f32_16x16x32_bf16 v[40:43], v[60:63], v[220:223], v[40:43]
	v_mfma_f32_16x16x32_bf16 v[28:31], v[52:55], v[232:235], v[28:31]
	v_mfma_f32_16x16x32_bf16 v[24:27], v[60:63], v[232:235], v[24:27]
	v_mfma_f32_16x16x32_bf16 v[12:15], v[52:55], v[240:243], v[12:15]
	v_mfma_f32_16x16x32_bf16 v[8:11], v[60:63], v[240:243], v[8:11]
	v_mfma_f32_16x16x32_bf16 v[36:39], v[182:185], v[216:219], v[36:39]
	v_mfma_f32_16x16x32_bf16 v[32:35], v[200:203], v[216:219], v[32:35]
	v_mfma_f32_16x16x32_bf16 v[20:23], v[182:185], v[228:231], v[20:23]
	v_mfma_f32_16x16x32_bf16 v[16:19], v[200:203], v[228:231], v[16:19]
	v_mfma_f32_16x16x32_bf16 v[4:7], v[182:185], v[236:239], v[4:7]
	v_mfma_f32_16x16x32_bf16 v[0:3], v[200:203], v[236:239], v[0:3]
	v_mfma_f32_16x16x32_bf16 v[48:51], v[182:185], v[208:211], v[68:71]
	v_mfma_f32_16x16x32_bf16 v[52:55], v[200:203], v[208:211], v[64:67]
	v_mfma_f32_16x16x32_bf16 v[36:39], v[186:189], v[220:223], v[36:39]
	v_mfma_f32_16x16x32_bf16 v[32:35], v[204:207], v[220:223], v[32:35]
	v_mfma_f32_16x16x32_bf16 v[20:23], v[186:189], v[232:235], v[20:23]
	v_mfma_f32_16x16x32_bf16 v[16:19], v[204:207], v[232:235], v[16:19]
	v_mfma_f32_16x16x32_bf16 v[4:7], v[186:189], v[240:243], v[4:7]
	v_mfma_f32_16x16x32_bf16 v[0:3], v[204:207], v[240:243], v[0:3]
	v_mfma_f32_16x16x32_bf16 v[48:51], v[186:189], v[212:215], v[48:51]
	v_mfma_f32_16x16x32_bf16 v[52:55], v[204:207], v[212:215], v[52:55]
	s_barrier
; #define PG8_STAGE(bufoff, gbase, voff) do { _Pragma("unroll") for (int _i = 0; _i < 2; ++_i) \
;         __builtin_amdgcn_global_load_lds((const unsigned*)((const char*)(gbase) + (voff)[_i]), (LAS unsigned*)(lds + (bufoff) + ldsw + _i * 8192), 16, 0, 0); } while (0)
; #define PG8_LDA(dst, b, h) do { _Pragma("unroll") for (int m = 0; m < 4; ++m) _Pragma("unroll") for (int k = 0; k < 2; ++k) dst[m][k] = *(const LAS bf16x8*)(lds + PG8_SA(b, h) + aoff + m * 2048 + k * 1024); } while (0)
; #define PG8_LDB(dst, b, h) do { _Pragma("unroll") for (int n = 0; n < 2; ++n) _Pragma("unroll") for (int k = 0; k < 2; ++k) dst[n][k] = *(const LAS bf16x8*)(lds + PG8_SB(b, h) + boff + n * 2048 + k * 1024); } while (0)
; #define PG8_MMA(ai, bj, At, Bt) do { __builtin_amdgcn_s_setprio(1); _Pragma("unroll") for (int m = 0; m < 4; ++m) _Pragma("unroll") for (int n = 0; n < 2; ++n) _Pragma("unroll") for (int k = 0; k < 2; ++k) \
;         acc[ai][bj][m][n] = __builtin_amdgcn_mfma_f32_16x16x32_bf16(Bt[n][k], At[m][k], acc[ai][bj][m][n], 0, 0, 0); __builtin_amdgcn_s_setprio(0); } while (0)
; #define PG8_WAIT_V(n) asm volatile("s_waitcnt vmcnt(" #n ")" ::: "memory")
; #define PG8_WAIT_L(n) asm volatile("s_waitcnt lgkmcnt(" #n ")" ::: "memory")
; #define PG8_BAR __builtin_amdgcn_s_barrier()
; #define PG8_SCHED __builtin_amdgcn_sched_barrier(0)
; template <class Epi, class Sched, bool ALIGN_EPI>
; DI void gemm_phase(LAS unsigned char* lds, const Gemm g, const Sched& S, const Epi& E) {
;     ...
;             PG8_LDB(B0, 1, 0); PG8_LDB(B1, 1, 1); PG8_SCHED; PG8_LDA(At, 1, 0); PG8_STAGE(PG8_SA(0, 1), a2 + hstep, voffA);
;             PG8_WAIT_V(8); PG8_WAIT_L(0); PG8_BAR; PG8_MMA(0, 0, At, B0); PG8_MMA(0, 1, At, B1); PG8_BAR; PG8_SCHED;
;             PG8_LDA(At, 1, 1); PG8_STAGE(PG8_SB(1, 0), b3, voffA); PG8_STAGE(PG8_SB(1, 1), b3 + hstep, voffA); PG8_STAGE(PG8_SA(1, 0), a3, voffA);
;             PG8_WAIT_V(8); PG8_WAIT_L(0); PG8_BAR; PG8_MMA(1, 0, At, B0); PG8_MMA(1, 1, At, B1); PG8_BAR; PG8_SCHED;
;         }
	s_add_i32 s48, 0, 0x18000
	s_add_i32 s49, 0, 0x1c000
	v_add_u32_e32 v68, s48, v157
	v_add_u32_e32 v150, s49, v157
	ds_read_b128 v[56:59], v68
	ds_read_b128 v[60:63], v68 offset:1024
	ds_read_b128 v[64:67], v68 offset:2048
	ds_read_b128 v[68:71], v68 offset:3072
	ds_read_b128 v[182:185], v150
	ds_read_b128 v[186:189], v150 offset:1024
	ds_read_b128 v[200:203], v150 offset:2048
	ds_read_b128 v[204:207], v150 offset:3072
	s_add_u32 s44, s44, 0x40000
	s_addc_u32 s45, s45, 0
	s_mov_b32 m0, s66
	ds_read_b128 v[208:211], v194 offset:32768
	ds_read_b128 v[212:215], v194 offset:33792
	ds_read_b128 v[216:219], v194 offset:34816
	ds_read_b128 v[220:223], v194 offset:35840
	ds_read_b128 v[228:231], v194 offset:36864
	ds_read_b128 v[232:235], v194 offset:37888
	ds_read_b128 v[236:239], v194 offset:38912
	ds_read_b128 v[240:243], v194 offset:39936
	global_load_lds_dwordx4 v146, s[44:45]
	s_mov_b32 m0, s67
	s_nop 0
	global_load_lds_dwordx4 v148, s[44:45]
	s_waitcnt vmcnt(8)
	s_waitcnt lgkmcnt(0)
	s_barrier
	s_waitcnt lgkmcnt(0)
	v_mfma_f32_16x16x32_bf16 v[140:143], v[56:59], v[208:211], v[140:143]
	v_mfma_f32_16x16x32_bf16 v[136:139], v[64:67], v[208:211], v[136:139]
	v_mfma_f32_16x16x32_bf16 v[124:127], v[56:59], v[216:219], v[124:127]
	v_mfma_f32_16x16x32_bf16 v[120:123], v[64:67], v[216:219], v[120:123]
	v_mfma_f32_16x16x32_bf16 v[108:111], v[56:59], v[228:231], v[108:111]
	v_mfma_f32_16x16x32_bf16 v[104:107], v[64:67], v[228:231], v[104:107]
	v_mfma_f32_16x16x32_bf16 v[92:95], v[56:59], v[236:239], v[92:95]
	v_mfma_f32_16x16x32_bf16 v[88:91], v[64:67], v[236:239], v[88:91]
	v_mfma_f32_16x16x32_bf16 v[140:143], v[60:63], v[212:215], v[140:143]
	v_mfma_f32_16x16x32_bf16 v[136:139], v[68:71], v[212:215], v[136:139]
	v_mfma_f32_16x16x32_bf16 v[124:127], v[60:63], v[220:223], v[124:127]
	v_mfma_f32_16x16x32_bf16 v[120:123], v[68:71], v[220:223], v[120:123]
	v_mfma_f32_16x16x32_bf16 v[108:111], v[60:63], v[232:235], v[108:111]
	v_mfma_f32_16x16x32_bf16 v[104:107], v[68:71], v[232:235], v[104:107]
	v_mfma_f32_16x16x32_bf16 v[92:95], v[60:63], v[240:243], v[92:95]
	v_mfma_f32_16x16x32_bf16 v[88:91], v[68:71], v[240:243], v[88:91]
	v_mfma_f32_16x16x32_bf16 v[132:135], v[182:185], v[208:211], v[132:135]
	v_mfma_f32_16x16x32_bf16 v[128:131], v[200:203], v[208:211], v[128:131]
	v_mfma_f32_16x16x32_bf16 v[116:119], v[182:185], v[216:219], v[116:119]
	v_mfma_f32_16x16x32_bf16 v[112:115], v[200:203], v[216:219], v[112:115]
	v_mfma_f32_16x16x32_bf16 v[100:103], v[182:185], v[228:231], v[100:103]
	v_mfma_f32_16x16x32_bf16 v[96:99], v[200:203], v[228:231], v[96:99]
	v_mfma_f32_16x16x32_bf16 v[84:87], v[182:185], v[236:239], v[84:87]
	v_mfma_f32_16x16x32_bf16 v[80:83], v[200:203], v[236:239], v[80:83]
	v_mfma_f32_16x16x32_bf16 v[132:135], v[186:189], v[212:215], v[132:135]
	v_mfma_f32_16x16x32_bf16 v[128:131], v[204:207], v[212:215], v[128:131]
	v_mfma_f32_16x16x32_bf16 v[116:119], v[186:189], v[220:223], v[116:119]
	v_mfma_f32_16x16x32_bf16 v[112:115], v[204:207], v[220:223], v[112:115]
	v_mfma_f32_16x16x32_bf16 v[100:103], v[186:189], v[232:235], v[100:103]
	v_mfma_f32_16x16x32_bf16 v[96:99], v[204:207], v[232:235], v[96:99]
	v_mfma_f32_16x16x32_bf16 v[84:87], v[186:189], v[240:243], v[84:87]
	v_mfma_f32_16x16x32_bf16 v[80:83], v[204:207], v[240:243], v[80:83]
	s_barrier
	s_add_i32 s44, s48, s63
	s_mov_b32 m0, s44
	ds_read_b128 v[208:211], v194 offset:49152
	ds_read_b128 v[212:215], v194 offset:50176
	ds_read_b128 v[216:219], v194 offset:51200
	ds_read_b128 v[220:223], v194 offset:52224
	ds_read_b128 v[228:231], v194 offset:53248
	ds_read_b128 v[232:235], v194 offset:54272
	ds_read_b128 v[236:239], v194 offset:55296
	ds_read_b128 v[240:243], v194 offset:56320
	global_load_lds_dwordx4 v146, s[94:95]
	s_add_i32 m0, s44, 0x2000
	s_add_u32 s8, s8, 0x40080
	s_addc_u32 s9, s9, 0
	s_add_i32 s44, s49, s63
	global_load_lds_dwordx4 v148, s[94:95]
	s_mov_b32 m0, s44
	s_nop 0
	global_load_lds_dwordx4 v146, s[8:9]
	s_add_i32 m0, s44, 0x2000
	s_nop 0
	global_load_lds_dwordx4 v148, s[8:9]
	s_mov_b32 m0, s70
	s_nop 0
	global_load_lds_dwordx4 v146, s[96:97]
	s_mov_b32 m0, s71
	s_nop 0
	global_load_lds_dwordx4 v148, s[96:97]
	s_waitcnt vmcnt(8)
	s_waitcnt lgkmcnt(0)
	s_barrier
	s_waitcnt lgkmcnt(0)
	v_mfma_f32_16x16x32_bf16 v[76:79], v[56:59], v[208:211], v[76:79]
	v_mfma_f32_16x16x32_bf16 v[72:75], v[64:67], v[208:211], v[72:75]
	v_mfma_f32_16x16x32_bf16 v[44:47], v[56:59], v[216:219], v[44:47]
	v_mfma_f32_16x16x32_bf16 v[40:43], v[64:67], v[216:219], v[40:43]
	v_mfma_f32_16x16x32_bf16 v[28:31], v[56:59], v[228:231], v[28:31]
	v_mfma_f32_16x16x32_bf16 v[24:27], v[64:67], v[228:231], v[24:27]
	v_mfma_f32_16x16x32_bf16 v[12:15], v[56:59], v[236:239], v[12:15]
	v_mfma_f32_16x16x32_bf16 v[8:11], v[64:67], v[236:239], v[8:11]
	v_mfma_f32_16x16x32_bf16 v[76:79], v[60:63], v[212:215], v[76:79]
	v_mfma_f32_16x16x32_bf16 v[72:75], v[68:71], v[212:215], v[72:75]
	v_mfma_f32_16x16x32_bf16 v[44:47], v[60:63], v[220:223], v[44:47]
	v_mfma_f32_16x16x32_bf16 v[40:43], v[68:71], v[220:223], v[40:43]
	v_mfma_f32_16x16x32_bf16 v[28:31], v[60:63], v[232:235], v[28:31]
	v_mfma_f32_16x16x32_bf16 v[24:27], v[68:71], v[232:235], v[24:27]
	v_mfma_f32_16x16x32_bf16 v[12:15], v[60:63], v[240:243], v[12:15]
	v_mfma_f32_16x16x32_bf16 v[8:11], v[68:71], v[240:243], v[8:11]
	v_mfma_f32_16x16x32_bf16 v[48:51], v[182:185], v[208:211], v[48:51]
	v_mfma_f32_16x16x32_bf16 v[68:71], v[186:189], v[212:215], v[48:51]
	v_mfma_f32_16x16x32_bf16 v[48:51], v[200:203], v[208:211], v[52:55]
	v_mfma_f32_16x16x32_bf16 v[36:39], v[182:185], v[216:219], v[36:39]
	v_mfma_f32_16x16x32_bf16 v[32:35], v[200:203], v[216:219], v[32:35]
	v_mfma_f32_16x16x32_bf16 v[20:23], v[182:185], v[228:231], v[20:23]
	v_mfma_f32_16x16x32_bf16 v[16:19], v[200:203], v[228:231], v[16:19]
	v_mfma_f32_16x16x32_bf16 v[4:7], v[182:185], v[236:239], v[4:7]
	v_mfma_f32_16x16x32_bf16 v[0:3], v[200:203], v[236:239], v[0:3]
	v_mfma_f32_16x16x32_bf16 v[64:67], v[204:207], v[212:215], v[48:51]
	v_mfma_f32_16x16x32_bf16 v[36:39], v[186:189], v[220:223], v[36:39]
	v_mfma_f32_16x16x32_bf16 v[32:35], v[204:207], v[220:223], v[32:35]
	v_mfma_f32_16x16x32_bf16 v[20:23], v[186:189], v[232:235], v[20:23]
	v_mfma_f32_16x16x32_bf16 v[16:19], v[204:207], v[232:235], v[16:19]
	v_mfma_f32_16x16x32_bf16 v[4:7], v[186:189], v[240:243], v[4:7]
	v_mfma_f32_16x16x32_bf16 v[0:3], v[204:207], v[240:243], v[0:3]
	s_barrier
	s_add_i32 s47, s47, 2
	s_add_u32 s0, s0, 0x100
	s_addc_u32 s1, s1, 0
	s_add_u32 s31, s31, 0x100
	s_addc_u32 s46, s46, 0
	s_cmp_gt_u32 s47, 13
	s_cbranch_scc0 .LBB0_104
	s_and_b64 vcc, exec, s[24:25]
	s_cbranch_vccz .LBB0_107
	s_barrier

; #define PG8_STAGE(bufoff, gbase, voff) do { _Pragma("unroll") for (int _i = 0; _i < 2; ++_i) \
;         __builtin_amdgcn_global_load_lds((const unsigned*)((const char*)(gbase) + (voff)[_i]), (LAS unsigned*)(lds + (bufoff) + ldsw + _i * 8192), 16, 0, 0); } while (0)
; #define PG8_LDA(dst, b, h) do { _Pragma("unroll") for (int m = 0; m < 4; ++m) _Pragma("unroll") for (int k = 0; k < 2; ++k) dst[m][k] = *(const LAS bf16x8*)(lds + PG8_SA(b, h) + aoff + m * 2048 + k * 1024); } while (0)
; #define PG8_LDB(dst, b, h) do { _Pragma("unroll") for (int n = 0; n < 2; ++n) _Pragma("unroll") for (int k = 0; k < 2; ++k) dst[n][k] = *(const LAS bf16x8*)(lds + PG8_SB(b, h) + boff + n * 2048 + k * 1024); } while (0)
; #define PG8_MMA(ai, bj, At, Bt) do { __builtin_amdgcn_s_setprio(1); _Pragma("unroll") for (int m = 0; m < 4; ++m) _Pragma("unroll") for (int n = 0; n < 2; ++n) _Pragma("unroll") for (int k = 0; k < 2; ++k) \
;         acc[ai][bj][m][n] = __builtin_amdgcn_mfma_f32_16x16x32_bf16(Bt[n][k], At[m][k], acc[ai][bj][m][n], 0, 0, 0); __builtin_amdgcn_s_setprio(0); } while (0)
; #define PG8_WAIT_V(n) asm volatile("s_waitcnt vmcnt(" #n ")" ::: "memory")
; #define PG8_WAIT_L(n) asm volatile("s_waitcnt lgkmcnt(" #n ")" ::: "memory")
; #define PG8_BAR __builtin_amdgcn_s_barrier()
; #define PG8_SCHED __builtin_amdgcn_sched_barrier(0)
; template <class Epi, class Sched, bool ALIGN_EPI>
; DI void gemm_phase(LAS unsigned char* lds, const Gemm g, const Sched& S, const Epi& E) {
;     ...
;             const bool last = (t == nt - 2);
;             const char* a1 = cA + (size_t)(t + 1) * kstep;
;             const char* a2 = last ? nA : cA + (size_t)(t + 2) * kstep; const char* b2 = last ? nB : cB + (size_t)(t + 2) * kstep;
;             const char* a3 = a2 + kstep; const char* b3 = b2 + kstep;
;             PG8_LDB(B0, 0, 0); PG8_LDB(B1, 0, 1); PG8_SCHED; PG8_LDA(At, 0, 0); PG8_STAGE(PG8_SA(1, 1), a1 + hstep, voffA);
;             PG8_WAIT_V(8); PG8_WAIT_L(0); PG8_BAR; PG8_MMA(0, 0, At, B0); PG8_MMA(0, 1, At, B1); PG8_BAR; PG8_SCHED;
;             PG8_LDA(At, 0, 1); PG8_STAGE(PG8_SB(0, 0), b2, voffA); PG8_STAGE(PG8_SB(0, 1), b2 + hstep, voffA); PG8_STAGE(PG8_SA(0, 0), a2, voffA);
;             PG8_WAIT_V(8); PG8_WAIT_L(0); PG8_BAR; PG8_MMA(1, 0, At, B0); PG8_MMA(1, 1, At, B1); PG8_BAR; PG8_SCHED;
.LBB0_791:
	s_add_u32 s16, s0, 0xfff50080
	s_addc_u32 s17, s1, -1
	s_add_i32 s42, 0, 0x10000
	s_cmp_eq_u32 s37, 40
	s_cselect_b32 s19, s13, s17
	s_cselect_b32 s18, s12, s16
	s_cselect_b32 s17, s5, s36
	s_cselect_b32 s16, s4, s35
	s_add_i32 s44, 0, 0x14000
	v_add_u32_e32 v140, s42, v165
	v_add_u32_e32 v156, s44, v165
	ds_read_b128 v[128:131], v140
	ds_read_b128 v[132:135], v140 offset:1024
	ds_read_b128 v[136:139], v140 offset:2048
	ds_read_b128 v[140:143], v140 offset:3072
	ds_read_b128 v[144:147], v156
	ds_read_b128 v[148:151], v156 offset:1024
	ds_read_b128 v[152:155], v156 offset:2048
	ds_read_b128 v[156:159], v156 offset:3072
	s_add_i32 m0, s23, 0xc000
	ds_read_b128 v[160:163], v167
	ds_read_b128 v[182:185], v167 offset:1024
	ds_read_b128 v[186:189], v167 offset:2048
	ds_read_b128 v[190:193], v167 offset:3072
	ds_read_b128 v[194:197], v167 offset:4096
	ds_read_b128 v[198:201], v167 offset:5120
	ds_read_b128 v[202:205], v167 offset:6144
	ds_read_b128 v[206:209], v167 offset:7168
	global_load_lds_dwordx4 v170, s[0:1]
	s_add_i32 m0, s23, 0xe000
	s_nop 0
	global_load_lds_dwordx4 v168, s[0:1]
	s_waitcnt vmcnt(8)
	s_waitcnt lgkmcnt(0)
	s_barrier
	s_waitcnt lgkmcnt(0)
	v_mfma_f32_16x16x32_bf16 v[124:127], v[128:131], v[160:163], v[124:127]
	v_mfma_f32_16x16x32_bf16 v[120:123], v[136:139], v[160:163], v[120:123]
	v_mfma_f32_16x16x32_bf16 v[108:111], v[128:131], v[186:189], v[108:111]
	v_mfma_f32_16x16x32_bf16 v[104:107], v[136:139], v[186:189], v[104:107]
	v_mfma_f32_16x16x32_bf16 v[96:99], v[128:131], v[194:197], v[96:99]
	v_mfma_f32_16x16x32_bf16 v[88:91], v[136:139], v[194:197], v[88:91]
	v_mfma_f32_16x16x32_bf16 v[80:83], v[128:131], v[202:205], v[80:83]
	v_mfma_f32_16x16x32_bf16 v[72:75], v[136:139], v[202:205], v[72:75]
	v_mfma_f32_16x16x32_bf16 v[124:127], v[132:135], v[182:185], v[124:127]
	v_mfma_f32_16x16x32_bf16 v[120:123], v[140:143], v[182:185], v[120:123]
	v_mfma_f32_16x16x32_bf16 v[108:111], v[132:135], v[190:193], v[108:111]
	v_mfma_f32_16x16x32_bf16 v[104:107], v[140:143], v[190:193], v[104:107]
	v_mfma_f32_16x16x32_bf16 v[96:99], v[132:135], v[198:201], v[96:99]
	v_mfma_f32_16x16x32_bf16 v[88:91], v[140:143], v[198:201], v[88:91]
	v_mfma_f32_16x16x32_bf16 v[80:83], v[132:135], v[206:209], v[80:83]
	v_mfma_f32_16x16x32_bf16 v[72:75], v[140:143], v[206:209], v[72:75]
	v_mfma_f32_16x16x32_bf16 v[116:119], v[144:147], v[160:163], v[116:119]
	v_mfma_f32_16x16x32_bf16 v[112:115], v[152:155], v[160:163], v[112:115]
	v_mfma_f32_16x16x32_bf16 v[100:103], v[144:147], v[186:189], v[100:103]
	v_mfma_f32_16x16x32_bf16 v[92:95], v[152:155], v[186:189], v[92:95]
	v_mfma_f32_16x16x32_bf16 v[84:87], v[144:147], v[194:197], v[84:87]
	v_mfma_f32_16x16x32_bf16 v[76:79], v[152:155], v[194:197], v[76:79]
	v_mfma_f32_16x16x32_bf16 v[68:71], v[144:147], v[202:205], v[68:71]
	v_mfma_f32_16x16x32_bf16 v[64:67], v[152:155], v[202:205], v[64:67]
	v_mfma_f32_16x16x32_bf16 v[116:119], v[148:151], v[182:185], v[116:119]
	v_mfma_f32_16x16x32_bf16 v[112:115], v[156:159], v[182:185], v[112:115]
	v_mfma_f32_16x16x32_bf16 v[100:103], v[148:151], v[190:193], v[100:103]
	v_mfma_f32_16x16x32_bf16 v[92:95], v[156:159], v[190:193], v[92:95]
	v_mfma_f32_16x16x32_bf16 v[84:87], v[148:151], v[198:201], v[84:87]
	v_mfma_f32_16x16x32_bf16 v[76:79], v[156:159], v[198:201], v[76:79]
	v_mfma_f32_16x16x32_bf16 v[68:71], v[148:151], v[206:209], v[68:71]
	v_mfma_f32_16x16x32_bf16 v[64:67], v[156:159], v[206:209], v[64:67]
	s_barrier
	s_add_i32 s42, s42, s20
	s_add_u32 s94, s16, s2
	s_addc_u32 s95, s17, s3
	s_add_u32 s96, s18, s2
	s_addc_u32 s97, s19, s3
	s_mov_b32 m0, s42
	ds_read_b128 v[160:163], v167 offset:16384
	ds_read_b128 v[182:185], v167 offset:17408
	ds_read_b128 v[186:189], v167 offset:18432
	ds_read_b128 v[190:193], v167 offset:19456
	ds_read_b128 v[194:197], v167 offset:20480
	ds_read_b128 v[198:201], v167 offset:21504
	ds_read_b128 v[202:205], v167 offset:22528
	ds_read_b128 v[206:209], v167 offset:23552
	global_load_lds_dwordx4 v170, s[16:17]
	s_add_i32 m0, s42, 0x2000
	s_add_u32 s42, s16, 0xb0000
	s_addc_u32 s43, s17, 0
	s_add_i32 s44, s44, s20
	global_load_lds_dwordx4 v168, s[16:17]
	s_mov_b32 m0, s44
	s_nop 0
	global_load_lds_dwordx4 v170, s[42:43]
	s_add_i32 m0, s44, 0x2000
	s_nop 0
	global_load_lds_dwordx4 v168, s[42:43]
	s_mov_b32 m0, s23
	s_nop 0
	global_load_lds_dwordx4 v170, s[18:19]
	s_mov_b32 m0, s24
	s_nop 0
	global_load_lds_dwordx4 v168, s[18:19]
	s_waitcnt vmcnt(8)
	s_waitcnt lgkmcnt(0)
	s_barrier
	s_waitcnt lgkmcnt(0)
	v_mfma_f32_16x16x32_bf16 v[60:63], v[128:131], v[160:163], v[60:63]
	v_mfma_f32_16x16x32_bf16 v[56:59], v[136:139], v[160:163], v[56:59]
	v_mfma_f32_16x16x32_bf16 v[48:51], v[128:131], v[186:189], v[48:51]
	v_mfma_f32_16x16x32_bf16 v[40:43], v[136:139], v[186:189], v[40:43]
	v_mfma_f32_16x16x32_bf16 v[32:35], v[128:131], v[194:197], v[32:35]
	v_mfma_f32_16x16x32_bf16 v[24:27], v[136:139], v[194:197], v[24:27]
	v_mfma_f32_16x16x32_bf16 v[16:19], v[128:131], v[202:205], v[16:19]
	v_mfma_f32_16x16x32_bf16 v[8:11], v[136:139], v[202:205], v[8:11]
	v_mfma_f32_16x16x32_bf16 v[60:63], v[132:135], v[182:185], v[60:63]
	v_mfma_f32_16x16x32_bf16 v[56:59], v[140:143], v[182:185], v[56:59]
	v_mfma_f32_16x16x32_bf16 v[48:51], v[132:135], v[190:193], v[48:51]
	v_mfma_f32_16x16x32_bf16 v[40:43], v[140:143], v[190:193], v[40:43]
	v_mfma_f32_16x16x32_bf16 v[32:35], v[132:135], v[198:201], v[32:35]
	v_mfma_f32_16x16x32_bf16 v[24:27], v[140:143], v[198:201], v[24:27]
	v_mfma_f32_16x16x32_bf16 v[16:19], v[132:135], v[206:209], v[16:19]
	v_mfma_f32_16x16x32_bf16 v[8:11], v[140:143], v[206:209], v[8:11]
	v_mfma_f32_16x16x32_bf16 v[52:55], v[144:147], v[160:163], v[52:55]
	v_mfma_f32_16x16x32_bf16 v[44:47], v[152:155], v[160:163], v[44:47]
	v_mfma_f32_16x16x32_bf16 v[36:39], v[144:147], v[186:189], v[36:39]
	v_mfma_f32_16x16x32_bf16 v[28:31], v[152:155], v[186:189], v[28:31]
	v_mfma_f32_16x16x32_bf16 v[20:23], v[144:147], v[194:197], v[20:23]
	v_mfma_f32_16x16x32_bf16 v[12:15], v[152:155], v[194:197], v[12:15]
	v_mfma_f32_16x16x32_bf16 v[4:7], v[144:147], v[202:205], v[4:7]
	v_mfma_f32_16x16x32_bf16 v[0:3], v[152:155], v[202:205], v[0:3]
	v_mfma_f32_16x16x32_bf16 v[52:55], v[148:151], v[182:185], v[52:55]
	v_mfma_f32_16x16x32_bf16 v[44:47], v[156:159], v[182:185], v[44:47]
	v_mfma_f32_16x16x32_bf16 v[36:39], v[148:151], v[190:193], v[36:39]
	v_mfma_f32_16x16x32_bf16 v[28:31], v[156:159], v[190:193], v[28:31]
	v_mfma_f32_16x16x32_bf16 v[20:23], v[148:151], v[198:201], v[20:23]
	v_mfma_f32_16x16x32_bf16 v[12:15], v[156:159], v[198:201], v[12:15]
	v_mfma_f32_16x16x32_bf16 v[4:7], v[148:151], v[206:209], v[4:7]
	v_mfma_f32_16x16x32_bf16 v[0:3], v[156:159], v[206:209], v[0:3]
	s_barrier
; #define PG8_STAGE(bufoff, gbase, voff) do { _Pragma("unroll") for (int _i = 0; _i < 2; ++_i) \
;         __builtin_amdgcn_global_load_lds((const unsigned*)((const char*)(gbase) + (voff)[_i]), (LAS unsigned*)(lds + (bufoff) + ldsw + _i * 8192), 16, 0, 0); } while (0)
; #define PG8_LDA(dst, b, h) do { _Pragma("unroll") for (int m = 0; m < 4; ++m) _Pragma("unroll") for (int k = 0; k < 2; ++k) dst[m][k] = *(const LAS bf16x8*)(lds + PG8_SA(b, h) + aoff + m * 2048 + k * 1024); } while (0)
; #define PG8_LDB(dst, b, h) do { _Pragma("unroll") for (int n = 0; n < 2; ++n) _Pragma("unroll") for (int k = 0; k < 2; ++k) dst[n][k] = *(const LAS bf16x8*)(lds + PG8_SB(b, h) + boff + n * 2048 + k * 1024); } while (0)
; #define PG8_MMA(ai, bj, At, Bt) do { __builtin_amdgcn_s_setprio(1); _Pragma("unroll") for (int m = 0; m < 4; ++m) _Pragma("unroll") for (int n = 0; n < 2; ++n) _Pragma("unroll") for (int k = 0; k < 2; ++k) \
;         acc[ai][bj][m][n] = __builtin_amdgcn_mfma_f32_16x16x32_bf16(Bt[n][k], At[m][k], acc[ai][bj][m][n], 0, 0, 0); __builtin_amdgcn_s_setprio(0); } while (0)
; #define PG8_WAIT_V(n) asm volatile("s_waitcnt vmcnt(" #n ")" ::: "memory")
; #define PG8_WAIT_L(n) asm volatile("s_waitcnt lgkmcnt(" #n ")" ::: "memory")
; #define PG8_BAR __builtin_amdgcn_s_barrier()
; #define PG8_SCHED __builtin_amdgcn_sched_barrier(0)
; template <class Epi, class Sched, bool ALIGN_EPI>
; DI void gemm_phase(LAS unsigned char* lds, const Gemm g, const Sched& S, const Epi& E) {
;     ...
;             PG8_LDB(B0, 1, 0); PG8_LDB(B1, 1, 1); PG8_SCHED; PG8_LDA(At, 1, 0); PG8_STAGE(PG8_SA(0, 1), a2 + hstep, voffA);
;             PG8_WAIT_V(8); PG8_WAIT_L(0); PG8_BAR; PG8_MMA(0, 0, At, B0); PG8_MMA(0, 1, At, B1); PG8_BAR; PG8_SCHED;
;             PG8_LDA(At, 1, 1); PG8_STAGE(PG8_SB(1, 0), b3, voffA); PG8_STAGE(PG8_SB(1, 1), b3 + hstep, voffA); PG8_STAGE(PG8_SA(1, 0), a3, voffA);
;             PG8_WAIT_V(8); PG8_WAIT_L(0); PG8_BAR; PG8_MMA(1, 0, At, B0); PG8_MMA(1, 1, At, B1); PG8_BAR; PG8_SCHED;
;         }
	s_add_i32 s42, 0, 0x18000
	s_add_i32 s43, 0, 0x1c000
	v_add_u32_e32 v140, s42, v165
	v_add_u32_e32 v156, s43, v165
	ds_read_b128 v[128:131], v140
	ds_read_b128 v[132:135], v140 offset:1024
	ds_read_b128 v[136:139], v140 offset:2048
	ds_read_b128 v[140:143], v140 offset:3072
	ds_read_b128 v[144:147], v156
	ds_read_b128 v[148:151], v156 offset:1024
	ds_read_b128 v[152:155], v156 offset:2048
	ds_read_b128 v[156:159], v156 offset:3072
	s_add_u32 s18, s18, 0xb0000
	s_addc_u32 s19, s19, 0
	s_mov_b32 m0, s25
	ds_read_b128 v[160:163], v167 offset:32768
	ds_read_b128 v[182:185], v167 offset:33792
	ds_read_b128 v[186:189], v167 offset:34816
	ds_read_b128 v[190:193], v167 offset:35840
	ds_read_b128 v[194:197], v167 offset:36864
	ds_read_b128 v[198:201], v167 offset:37888
	ds_read_b128 v[202:205], v167 offset:38912
	ds_read_b128 v[206:209], v167 offset:39936
	global_load_lds_dwordx4 v170, s[18:19]
	s_mov_b32 m0, s26
	s_nop 0
	global_load_lds_dwordx4 v168, s[18:19]
	s_waitcnt vmcnt(8)
	s_waitcnt lgkmcnt(0)
	s_barrier
	s_waitcnt lgkmcnt(0)
	v_mfma_f32_16x16x32_bf16 v[124:127], v[128:131], v[160:163], v[124:127]
	v_mfma_f32_16x16x32_bf16 v[120:123], v[136:139], v[160:163], v[120:123]
	v_mfma_f32_16x16x32_bf16 v[108:111], v[128:131], v[186:189], v[108:111]
	v_mfma_f32_16x16x32_bf16 v[104:107], v[136:139], v[186:189], v[104:107]
	v_mfma_f32_16x16x32_bf16 v[96:99], v[128:131], v[194:197], v[96:99]
	v_mfma_f32_16x16x32_bf16 v[88:91], v[136:139], v[194:197], v[88:91]
	v_mfma_f32_16x16x32_bf16 v[80:83], v[128:131], v[202:205], v[80:83]
	v_mfma_f32_16x16x32_bf16 v[72:75], v[136:139], v[202:205], v[72:75]
	v_mfma_f32_16x16x32_bf16 v[124:127], v[132:135], v[182:185], v[124:127]
	v_mfma_f32_16x16x32_bf16 v[120:123], v[140:143], v[182:185], v[120:123]
	v_mfma_f32_16x16x32_bf16 v[108:111], v[132:135], v[190:193], v[108:111]
	v_mfma_f32_16x16x32_bf16 v[104:107], v[140:143], v[190:193], v[104:107]
	v_mfma_f32_16x16x32_bf16 v[96:99], v[132:135], v[198:201], v[96:99]
	v_mfma_f32_16x16x32_bf16 v[88:91], v[140:143], v[198:201], v[88:91]
	v_mfma_f32_16x16x32_bf16 v[80:83], v[132:135], v[206:209], v[80:83]
	v_mfma_f32_16x16x32_bf16 v[72:75], v[140:143], v[206:209], v[72:75]
	v_mfma_f32_16x16x32_bf16 v[116:119], v[144:147], v[160:163], v[116:119]
	v_mfma_f32_16x16x32_bf16 v[112:115], v[152:155], v[160:163], v[112:115]
	v_mfma_f32_16x16x32_bf16 v[100:103], v[144:147], v[186:189], v[100:103]
	v_mfma_f32_16x16x32_bf16 v[92:95], v[152:155], v[186:189], v[92:95]
	v_mfma_f32_16x16x32_bf16 v[84:87], v[144:147], v[194:197], v[84:87]
	v_mfma_f32_16x16x32_bf16 v[76:79], v[152:155], v[194:197], v[76:79]
	v_mfma_f32_16x16x32_bf16 v[68:71], v[144:147], v[202:205], v[68:71]
	v_mfma_f32_16x16x32_bf16 v[64:67], v[152:155], v[202:205], v[64:67]
	v_mfma_f32_16x16x32_bf16 v[116:119], v[148:151], v[182:185], v[116:119]
	v_mfma_f32_16x16x32_bf16 v[112:115], v[156:159], v[182:185], v[112:115]
	v_mfma_f32_16x16x32_bf16 v[100:103], v[148:151], v[190:193], v[100:103]
	v_mfma_f32_16x16x32_bf16 v[92:95], v[156:159], v[190:193], v[92:95]
	v_mfma_f32_16x16x32_bf16 v[84:87], v[148:151], v[198:201], v[84:87]
	v_mfma_f32_16x16x32_bf16 v[76:79], v[156:159], v[198:201], v[76:79]
	v_mfma_f32_16x16x32_bf16 v[68:71], v[148:151], v[206:209], v[68:71]
	v_mfma_f32_16x16x32_bf16 v[64:67], v[156:159], v[206:209], v[64:67]
	s_barrier
	s_add_i32 s18, s42, s20
	s_mov_b32 m0, s18
	ds_read_b128 v[160:163], v167 offset:49152
	ds_read_b128 v[182:185], v167 offset:50176
	ds_read_b128 v[186:189], v167 offset:51200
	ds_read_b128 v[190:193], v167 offset:52224
	ds_read_b128 v[194:197], v167 offset:53248
	ds_read_b128 v[198:201], v167 offset:54272
	ds_read_b128 v[202:205], v167 offset:55296
	ds_read_b128 v[206:209], v167 offset:56320
	global_load_lds_dwordx4 v170, s[94:95]
	s_add_i32 m0, s18, 0x2000
	s_add_u32 s16, s16, 0xb0080
	s_addc_u32 s17, s17, 0
	s_add_i32 s18, s43, s20
	global_load_lds_dwordx4 v168, s[94:95]
	s_mov_b32 m0, s18
	s_nop 0
	global_load_lds_dwordx4 v170, s[16:17]
	s_add_i32 m0, s18, 0x2000
	s_nop 0
	global_load_lds_dwordx4 v168, s[16:17]
	s_mov_b32 m0, s27
	s_nop 0
	global_load_lds_dwordx4 v170, s[96:97]
	s_mov_b32 m0, s28
	s_nop 0
	global_load_lds_dwordx4 v168, s[96:97]
	s_waitcnt vmcnt(8)
	s_waitcnt lgkmcnt(0)
	s_barrier
	s_waitcnt lgkmcnt(0)
	v_mfma_f32_16x16x32_bf16 v[60:63], v[128:131], v[160:163], v[60:63]
	v_mfma_f32_16x16x32_bf16 v[56:59], v[136:139], v[160:163], v[56:59]
	v_mfma_f32_16x16x32_bf16 v[48:51], v[128:131], v[186:189], v[48:51]
	v_mfma_f32_16x16x32_bf16 v[40:43], v[136:139], v[186:189], v[40:43]
	v_mfma_f32_16x16x32_bf16 v[32:35], v[128:131], v[194:197], v[32:35]
	v_mfma_f32_16x16x32_bf16 v[24:27], v[136:139], v[194:197], v[24:27]
	v_mfma_f32_16x16x32_bf16 v[16:19], v[128:131], v[202:205], v[16:19]
	v_mfma_f32_16x16x32_bf16 v[8:11], v[136:139], v[202:205], v[8:11]
	v_mfma_f32_16x16x32_bf16 v[60:63], v[132:135], v[182:185], v[60:63]
	v_mfma_f32_16x16x32_bf16 v[56:59], v[140:143], v[182:185], v[56:59]
	v_mfma_f32_16x16x32_bf16 v[48:51], v[132:135], v[190:193], v[48:51]
	v_mfma_f32_16x16x32_bf16 v[40:43], v[140:143], v[190:193], v[40:43]
	v_mfma_f32_16x16x32_bf16 v[32:35], v[132:135], v[198:201], v[32:35]
	v_mfma_f32_16x16x32_bf16 v[24:27], v[140:143], v[198:201], v[24:27]
	v_mfma_f32_16x16x32_bf16 v[16:19], v[132:135], v[206:209], v[16:19]
	v_mfma_f32_16x16x32_bf16 v[8:11], v[140:143], v[206:209], v[8:11]
	v_mfma_f32_16x16x32_bf16 v[52:55], v[144:147], v[160:163], v[52:55]
	v_mfma_f32_16x16x32_bf16 v[44:47], v[152:155], v[160:163], v[44:47]
	v_mfma_f32_16x16x32_bf16 v[36:39], v[144:147], v[186:189], v[36:39]
	v_mfma_f32_16x16x32_bf16 v[28:31], v[152:155], v[186:189], v[28:31]
	v_mfma_f32_16x16x32_bf16 v[20:23], v[144:147], v[194:197], v[20:23]
	v_mfma_f32_16x16x32_bf16 v[12:15], v[152:155], v[194:197], v[12:15]
	v_mfma_f32_16x16x32_bf16 v[4:7], v[144:147], v[202:205], v[4:7]
	v_mfma_f32_16x16x32_bf16 v[0:3], v[152:155], v[202:205], v[0:3]
	v_mfma_f32_16x16x32_bf16 v[52:55], v[148:151], v[182:185], v[52:55]
	v_mfma_f32_16x16x32_bf16 v[44:47], v[156:159], v[182:185], v[44:47]
	v_mfma_f32_16x16x32_bf16 v[36:39], v[148:151], v[190:193], v[36:39]
	v_mfma_f32_16x16x32_bf16 v[28:31], v[156:159], v[190:193], v[28:31]
	v_mfma_f32_16x16x32_bf16 v[20:23], v[148:151], v[198:201], v[20:23]
	v_mfma_f32_16x16x32_bf16 v[12:15], v[156:159], v[198:201], v[12:15]
	v_mfma_f32_16x16x32_bf16 v[4:7], v[148:151], v[206:209], v[4:7]
	v_mfma_f32_16x16x32_bf16 v[0:3], v[156:159], v[206:209], v[0:3]
	s_barrier
	s_add_i32 s37, s37, 2
	s_add_u32 s0, s0, 0x100
	s_addc_u32 s1, s1, 0
	s_add_u32 s35, s35, 0x100
	s_addc_u32 s36, s36, 0
	s_cmp_gt_u32 s37, 41
	s_cbranch_scc0 .LBB0_791
	s_and_b64 vcc, exec, s[10:11]
	s_cbranch_vccz .LBB0_794
	s_barrier

; #define PG8_STAGE(bufoff, gbase, voff) do { _Pragma("unroll") for (int _i = 0; _i < 2; ++_i) \
;         __builtin_amdgcn_global_load_lds((const unsigned*)((const char*)(gbase) + (voff)[_i]), (LAS unsigned*)(lds + (bufoff) + ldsw + _i * 8192), 16, 0, 0); } while (0)
; #define PG8_LDA(dst, b, h) do { _Pragma("unroll") for (int m = 0; m < 4; ++m) _Pragma("unroll") for (int k = 0; k < 2; ++k) dst[m][k] = *(const LAS bf16x8*)(lds + PG8_SA(b, h) + aoff + m * 2048 + k * 1024); } while (0)
; #define PG8_LDB(dst, b, h) do { _Pragma("unroll") for (int n = 0; n < 2; ++n) _Pragma("unroll") for (int k = 0; k < 2; ++k) dst[n][k] = *(const LAS bf16x8*)(lds + PG8_SB(b, h) + boff + n * 2048 + k * 1024); } while (0)
; #define PG8_MMA(ai, bj, At, Bt) do { __builtin_amdgcn_s_setprio(1); _Pragma("unroll") for (int m = 0; m < 4; ++m) _Pragma("unroll") for (int n = 0; n < 2; ++n) _Pragma("unroll") for (int k = 0; k < 2; ++k) \
;         acc[ai][bj][m][n] = __builtin_amdgcn_mfma_f32_16x16x32_bf16(Bt[n][k], At[m][k], acc[ai][bj][m][n], 0, 0, 0); __builtin_amdgcn_s_setprio(0); } while (0)
; #define PG8_WAIT_V(n) asm volatile("s_waitcnt vmcnt(" #n ")" ::: "memory")
; #define PG8_WAIT_L(n) asm volatile("s_waitcnt lgkmcnt(" #n ")" ::: "memory")
; #define PG8_BAR __builtin_amdgcn_s_barrier()
; #define PG8_SCHED __builtin_amdgcn_sched_barrier(0)
; template <class Epi, class Sched, bool ALIGN_EPI>
; DI void gemm_phase(LAS unsigned char* lds, const Gemm g, const Sched& S, const Epi& E) {
;     ...
;             const bool last = (t == nt - 2);
;             const char* a1 = cA + (size_t)(t + 1) * kstep;
;             const char* a2 = last ? nA : cA + (size_t)(t + 2) * kstep; const char* b2 = last ? nB : cB + (size_t)(t + 2) * kstep;
;             const char* a3 = a2 + kstep; const char* b3 = b2 + kstep;
;             PG8_LDB(B0, 0, 0); PG8_LDB(B1, 0, 1); PG8_SCHED; PG8_LDA(At, 0, 0); PG8_STAGE(PG8_SA(1, 1), a1 + hstep, voffA);
;             PG8_WAIT_V(8); PG8_WAIT_L(0); PG8_BAR; PG8_MMA(0, 0, At, B0); PG8_MMA(0, 1, At, B1); PG8_BAR; PG8_SCHED;
;             PG8_LDA(At, 0, 1); PG8_STAGE(PG8_SB(0, 0), b2, voffA); PG8_STAGE(PG8_SB(0, 1), b2 + hstep, voffA); PG8_STAGE(PG8_SA(0, 0), a2, voffA);
;             PG8_WAIT_V(8); PG8_WAIT_L(0); PG8_BAR; PG8_MMA(1, 0, At, B0); PG8_MMA(1, 1, At, B1); PG8_BAR; PG8_SCHED;
.LBB0_826:
	s_add_u32 s30, s0, 0xfffc0080
	s_addc_u32 s31, s1, -1
	s_add_i32 s46, 0, 0x10000
	s_cmp_eq_u32 s45, 12
	s_cselect_b32 s35, s25, s31
	s_cselect_b32 s34, s24, s30
	s_cselect_b32 s31, s23, s44
	s_cselect_b32 s30, s29, s43
	s_add_i32 s52, 0, 0x14000
	ds_read_b128 v[44:47], v206
	ds_read_b128 v[48:51], v206 offset:1024
	ds_read_b128 v[52:55], v206 offset:2048
	ds_read_b128 v[56:59], v206 offset:3072
	ds_read_b128 v[124:127], v206 offset:16384
	ds_read_b128 v[128:131], v206 offset:17408
	ds_read_b128 v[132:135], v206 offset:18432
	ds_read_b128 v[136:139], v206 offset:19456
	s_add_i32 m0, s93, 0xc000
	ds_read_b128 v[160:163], v245
	ds_read_b128 v[164:167], v245 offset:1024
	ds_read_b128 v[182:185], v245 offset:2048
	ds_read_b128 v[186:189], v245 offset:3072
	ds_read_b128 v[190:193], v245 offset:4096
	ds_read_b128 v[194:197], v245 offset:5120
	ds_read_b128 v[198:201], v245 offset:6144
	ds_read_b128 v[202:205], v245 offset:7168
	global_load_lds_dwordx4 v178, s[0:1]
	s_add_i32 m0, s93, 0xe000
	s_nop 0
	global_load_lds_dwordx4 v180, s[0:1]
	s_waitcnt vmcnt(8)
	s_waitcnt lgkmcnt(0)
	s_barrier
	s_waitcnt lgkmcnt(0)
	v_mfma_f32_16x16x32_bf16 v[156:159], v[44:47], v[160:163], v[156:159]
	v_mfma_f32_16x16x32_bf16 v[76:79], v[52:55], v[160:163], v[76:79]
	v_mfma_f32_16x16x32_bf16 v[148:151], v[44:47], v[182:185], v[148:151]
	v_mfma_f32_16x16x32_bf16 v[68:71], v[52:55], v[182:185], v[68:71]
	v_mfma_f32_16x16x32_bf16 v[140:143], v[44:47], v[190:193], v[140:143]
	v_mfma_f32_16x16x32_bf16 v[60:63], v[52:55], v[190:193], v[60:63]
	v_mfma_f32_16x16x32_bf16 v[116:119], v[44:47], v[198:201], v[116:119]
	v_mfma_f32_16x16x32_bf16 v[36:39], v[52:55], v[198:201], v[36:39]
	v_mfma_f32_16x16x32_bf16 v[156:159], v[48:51], v[164:167], v[156:159]
	v_mfma_f32_16x16x32_bf16 v[76:79], v[56:59], v[164:167], v[76:79]
	v_mfma_f32_16x16x32_bf16 v[148:151], v[48:51], v[186:189], v[148:151]
	v_mfma_f32_16x16x32_bf16 v[68:71], v[56:59], v[186:189], v[68:71]
	v_mfma_f32_16x16x32_bf16 v[140:143], v[48:51], v[194:197], v[140:143]
	v_mfma_f32_16x16x32_bf16 v[60:63], v[56:59], v[194:197], v[60:63]
	v_mfma_f32_16x16x32_bf16 v[116:119], v[48:51], v[202:205], v[116:119]
	v_mfma_f32_16x16x32_bf16 v[36:39], v[56:59], v[202:205], v[36:39]
	v_mfma_f32_16x16x32_bf16 v[152:155], v[124:127], v[160:163], v[152:155]
	v_mfma_f32_16x16x32_bf16 v[72:75], v[132:135], v[160:163], v[72:75]
	v_mfma_f32_16x16x32_bf16 v[144:147], v[124:127], v[182:185], v[144:147]
	v_mfma_f32_16x16x32_bf16 v[64:67], v[132:135], v[182:185], v[64:67]
	v_mfma_f32_16x16x32_bf16 v[120:123], v[124:127], v[190:193], v[120:123]
	v_mfma_f32_16x16x32_bf16 v[40:43], v[132:135], v[190:193], v[40:43]
	v_mfma_f32_16x16x32_bf16 v[112:115], v[124:127], v[198:201], v[112:115]
	v_mfma_f32_16x16x32_bf16 v[32:35], v[132:135], v[198:201], v[32:35]
	v_mfma_f32_16x16x32_bf16 v[152:155], v[128:131], v[164:167], v[152:155]
	v_mfma_f32_16x16x32_bf16 v[72:75], v[136:139], v[164:167], v[72:75]
	v_mfma_f32_16x16x32_bf16 v[144:147], v[128:131], v[186:189], v[144:147]
	v_mfma_f32_16x16x32_bf16 v[64:67], v[136:139], v[186:189], v[64:67]
	v_mfma_f32_16x16x32_bf16 v[120:123], v[128:131], v[194:197], v[120:123]
	v_mfma_f32_16x16x32_bf16 v[40:43], v[136:139], v[194:197], v[40:43]
	v_mfma_f32_16x16x32_bf16 v[112:115], v[128:131], v[202:205], v[112:115]
	v_mfma_f32_16x16x32_bf16 v[32:35], v[136:139], v[202:205], v[32:35]
	s_barrier
	s_add_i32 s46, s46, s92
	s_add_u32 s94, s30, s2
	s_addc_u32 s95, s31, s3
	s_add_u32 s96, s34, s2
	s_addc_u32 s97, s35, s3
	s_mov_b32 m0, s46
	ds_read_b128 v[160:163], v245 offset:16384
	ds_read_b128 v[164:167], v245 offset:17408
	ds_read_b128 v[182:185], v245 offset:18432
	ds_read_b128 v[186:189], v245 offset:19456
	ds_read_b128 v[190:193], v245 offset:20480
	ds_read_b128 v[194:197], v245 offset:21504
	ds_read_b128 v[198:201], v245 offset:22528
	ds_read_b128 v[202:205], v245 offset:23552
	global_load_lds_dwordx4 v174, s[30:31]
	s_add_i32 m0, s46, 0x2000
	s_add_u32 s46, s30, 0x40000
	s_addc_u32 s47, s31, 0
	s_add_i32 s52, s52, s92
	global_load_lds_dwordx4 v176, s[30:31]
	s_mov_b32 m0, s52
	s_nop 0
	global_load_lds_dwordx4 v174, s[46:47]
	s_add_i32 m0, s52, 0x2000
	s_nop 0
	global_load_lds_dwordx4 v176, s[46:47]
	s_mov_b32 m0, s93
	s_nop 0
	global_load_lds_dwordx4 v174, s[34:35]
	s_mov_b32 m0, s86
	s_nop 0
	global_load_lds_dwordx4 v176, s[34:35]
	s_waitcnt vmcnt(8)
	s_waitcnt lgkmcnt(0)
	s_barrier
	s_waitcnt lgkmcnt(0)
	v_mfma_f32_16x16x32_bf16 v[108:111], v[44:47], v[160:163], v[108:111]
	v_mfma_f32_16x16x32_bf16 v[28:31], v[52:55], v[160:163], v[28:31]
	v_mfma_f32_16x16x32_bf16 v[100:103], v[44:47], v[182:185], v[100:103]
	v_mfma_f32_16x16x32_bf16 v[20:23], v[52:55], v[182:185], v[20:23]
	v_mfma_f32_16x16x32_bf16 v[92:95], v[44:47], v[190:193], v[92:95]
	v_mfma_f32_16x16x32_bf16 v[12:15], v[52:55], v[190:193], v[12:15]
	v_mfma_f32_16x16x32_bf16 v[4:7], v[52:55], v[198:201], v[4:7]
	v_mfma_f32_16x16x32_bf16 v[108:111], v[48:51], v[164:167], v[108:111]
	v_mfma_f32_16x16x32_bf16 v[28:31], v[56:59], v[164:167], v[28:31]
	v_mfma_f32_16x16x32_bf16 v[100:103], v[48:51], v[186:189], v[100:103]
	v_mfma_f32_16x16x32_bf16 v[20:23], v[56:59], v[186:189], v[20:23]
	v_mfma_f32_16x16x32_bf16 v[92:95], v[48:51], v[194:197], v[92:95]
	v_mfma_f32_16x16x32_bf16 v[12:15], v[56:59], v[194:197], v[12:15]
	v_mfma_f32_16x16x32_bf16 v[44:47], v[44:47], v[198:201], v[84:87]
	v_mfma_f32_16x16x32_bf16 v[4:7], v[56:59], v[202:205], v[4:7]
	v_mfma_f32_16x16x32_bf16 v[44:47], v[48:51], v[202:205], v[44:47]
	v_mfma_f32_16x16x32_bf16 v[24:27], v[132:135], v[160:163], v[24:27]
	v_mfma_f32_16x16x32_bf16 v[16:19], v[132:135], v[182:185], v[16:19]
	v_mfma_f32_16x16x32_bf16 v[8:11], v[132:135], v[190:193], v[8:11]
	v_mfma_f32_16x16x32_bf16 v[80:83], v[124:127], v[198:201], v[80:83]
	v_mfma_f32_16x16x32_bf16 v[0:3], v[132:135], v[198:201], v[0:3]
	v_mfma_f32_16x16x32_bf16 v[48:51], v[124:127], v[160:163], v[104:107]
	v_mfma_f32_16x16x32_bf16 v[24:27], v[136:139], v[164:167], v[24:27]
	v_mfma_f32_16x16x32_bf16 v[52:55], v[124:127], v[182:185], v[96:99]
	v_mfma_f32_16x16x32_bf16 v[16:19], v[136:139], v[186:189], v[16:19]
	v_mfma_f32_16x16x32_bf16 v[56:59], v[124:127], v[190:193], v[88:91]
	v_mfma_f32_16x16x32_bf16 v[8:11], v[136:139], v[194:197], v[8:11]
	v_mfma_f32_16x16x32_bf16 v[80:83], v[128:131], v[202:205], v[80:83]
	v_mfma_f32_16x16x32_bf16 v[0:3], v[136:139], v[202:205], v[0:3]
	v_mfma_f32_16x16x32_bf16 v[48:51], v[128:131], v[164:167], v[48:51]
	v_mfma_f32_16x16x32_bf16 v[52:55], v[128:131], v[186:189], v[52:55]
	v_mfma_f32_16x16x32_bf16 v[56:59], v[128:131], v[194:197], v[56:59]
	s_barrier
; #define PG8_STAGE(bufoff, gbase, voff) do { _Pragma("unroll") for (int _i = 0; _i < 2; ++_i) \
;         __builtin_amdgcn_global_load_lds((const unsigned*)((const char*)(gbase) + (voff)[_i]), (LAS unsigned*)(lds + (bufoff) + ldsw + _i * 8192), 16, 0, 0); } while (0)
; #define PG8_LDA(dst, b, h) do { _Pragma("unroll") for (int m = 0; m < 4; ++m) _Pragma("unroll") for (int k = 0; k < 2; ++k) dst[m][k] = *(const LAS bf16x8*)(lds + PG8_SA(b, h) + aoff + m * 2048 + k * 1024); } while (0)
; #define PG8_LDB(dst, b, h) do { _Pragma("unroll") for (int n = 0; n < 2; ++n) _Pragma("unroll") for (int k = 0; k < 2; ++k) dst[n][k] = *(const LAS bf16x8*)(lds + PG8_SB(b, h) + boff + n * 2048 + k * 1024); } while (0)
; #define PG8_MMA(ai, bj, At, Bt) do { __builtin_amdgcn_s_setprio(1); _Pragma("unroll") for (int m = 0; m < 4; ++m) _Pragma("unroll") for (int n = 0; n < 2; ++n) _Pragma("unroll") for (int k = 0; k < 2; ++k) \
;         acc[ai][bj][m][n] = __builtin_amdgcn_mfma_f32_16x16x32_bf16(Bt[n][k], At[m][k], acc[ai][bj][m][n], 0, 0, 0); __builtin_amdgcn_s_setprio(0); } while (0)
; #define PG8_WAIT_V(n) asm volatile("s_waitcnt vmcnt(" #n ")" ::: "memory")
; #define PG8_WAIT_L(n) asm volatile("s_waitcnt lgkmcnt(" #n ")" ::: "memory")
; #define PG8_BAR __builtin_amdgcn_s_barrier()
; #define PG8_SCHED __builtin_amdgcn_sched_barrier(0)
; template <class Epi, class Sched, bool ALIGN_EPI>
; DI void gemm_phase(LAS unsigned char* lds, const Gemm g, const Sched& S, const Epi& E) {
;     ...
;             PG8_LDB(B0, 1, 0); PG8_LDB(B1, 1, 1); PG8_SCHED; PG8_LDA(At, 1, 0); PG8_STAGE(PG8_SA(0, 1), a2 + hstep, voffA);
;             PG8_WAIT_V(8); PG8_WAIT_L(0); PG8_BAR; PG8_MMA(0, 0, At, B0); PG8_MMA(0, 1, At, B1); PG8_BAR; PG8_SCHED;
;             PG8_LDA(At, 1, 1); PG8_STAGE(PG8_SB(1, 0), b3, voffA); PG8_STAGE(PG8_SB(1, 1), b3 + hstep, voffA); PG8_STAGE(PG8_SA(1, 0), a3, voffA);
;             PG8_WAIT_V(8); PG8_WAIT_L(0); PG8_BAR; PG8_MMA(1, 0, At, B0); PG8_MMA(1, 1, At, B1); PG8_BAR; PG8_SCHED;
;         }
	s_add_i32 s46, 0, 0x18000
	s_add_i32 s47, 0, 0x1c000
	ds_read_b128 v[84:87], v206 offset:32768
	ds_read_b128 v[88:91], v206 offset:33792
	ds_read_b128 v[96:99], v206 offset:34816
	ds_read_b128 v[104:107], v206 offset:35840
	ds_read_b128 v[124:127], v206 offset:49152
	ds_read_b128 v[128:131], v206 offset:50176
	ds_read_b128 v[132:135], v206 offset:51200
	ds_read_b128 v[136:139], v206 offset:52224
	s_add_u32 s34, s34, 0x40000
	s_addc_u32 s35, s35, 0
	s_mov_b32 m0, s33
	ds_read_b128 v[160:163], v245 offset:32768
	ds_read_b128 v[164:167], v245 offset:33792
	ds_read_b128 v[182:185], v245 offset:34816
	ds_read_b128 v[186:189], v245 offset:35840
	ds_read_b128 v[190:193], v245 offset:36864
	ds_read_b128 v[194:197], v245 offset:37888
	ds_read_b128 v[198:201], v245 offset:38912
	ds_read_b128 v[202:205], v245 offset:39936
	global_load_lds_dwordx4 v174, s[34:35]
	s_mov_b32 m0, s78
	s_nop 0
	global_load_lds_dwordx4 v176, s[34:35]
	s_waitcnt vmcnt(8)
	s_waitcnt lgkmcnt(0)
	s_barrier
	s_waitcnt lgkmcnt(0)
	v_mfma_f32_16x16x32_bf16 v[156:159], v[84:87], v[160:163], v[156:159]
	v_mfma_f32_16x16x32_bf16 v[76:79], v[96:99], v[160:163], v[76:79]
	v_mfma_f32_16x16x32_bf16 v[148:151], v[84:87], v[182:185], v[148:151]
	v_mfma_f32_16x16x32_bf16 v[68:71], v[96:99], v[182:185], v[68:71]
	v_mfma_f32_16x16x32_bf16 v[140:143], v[84:87], v[190:193], v[140:143]
	v_mfma_f32_16x16x32_bf16 v[60:63], v[96:99], v[190:193], v[60:63]
	v_mfma_f32_16x16x32_bf16 v[116:119], v[84:87], v[198:201], v[116:119]
	v_mfma_f32_16x16x32_bf16 v[36:39], v[96:99], v[198:201], v[36:39]
	v_mfma_f32_16x16x32_bf16 v[156:159], v[88:91], v[164:167], v[156:159]
	v_mfma_f32_16x16x32_bf16 v[76:79], v[104:107], v[164:167], v[76:79]
	v_mfma_f32_16x16x32_bf16 v[148:151], v[88:91], v[186:189], v[148:151]
	v_mfma_f32_16x16x32_bf16 v[68:71], v[104:107], v[186:189], v[68:71]
	v_mfma_f32_16x16x32_bf16 v[140:143], v[88:91], v[194:197], v[140:143]
	v_mfma_f32_16x16x32_bf16 v[60:63], v[104:107], v[194:197], v[60:63]
	v_mfma_f32_16x16x32_bf16 v[116:119], v[88:91], v[202:205], v[116:119]
	v_mfma_f32_16x16x32_bf16 v[36:39], v[104:107], v[202:205], v[36:39]
	v_mfma_f32_16x16x32_bf16 v[152:155], v[124:127], v[160:163], v[152:155]
	v_mfma_f32_16x16x32_bf16 v[72:75], v[132:135], v[160:163], v[72:75]
	v_mfma_f32_16x16x32_bf16 v[144:147], v[124:127], v[182:185], v[144:147]
	v_mfma_f32_16x16x32_bf16 v[64:67], v[132:135], v[182:185], v[64:67]
	v_mfma_f32_16x16x32_bf16 v[120:123], v[124:127], v[190:193], v[120:123]
	v_mfma_f32_16x16x32_bf16 v[40:43], v[132:135], v[190:193], v[40:43]
	v_mfma_f32_16x16x32_bf16 v[112:115], v[124:127], v[198:201], v[112:115]
	v_mfma_f32_16x16x32_bf16 v[32:35], v[132:135], v[198:201], v[32:35]
	v_mfma_f32_16x16x32_bf16 v[152:155], v[128:131], v[164:167], v[152:155]
	v_mfma_f32_16x16x32_bf16 v[72:75], v[136:139], v[164:167], v[72:75]
	v_mfma_f32_16x16x32_bf16 v[144:147], v[128:131], v[186:189], v[144:147]
	v_mfma_f32_16x16x32_bf16 v[64:67], v[136:139], v[186:189], v[64:67]
	v_mfma_f32_16x16x32_bf16 v[120:123], v[128:131], v[194:197], v[120:123]
	v_mfma_f32_16x16x32_bf16 v[40:43], v[136:139], v[194:197], v[40:43]
	v_mfma_f32_16x16x32_bf16 v[112:115], v[128:131], v[202:205], v[112:115]
	v_mfma_f32_16x16x32_bf16 v[32:35], v[136:139], v[202:205], v[32:35]
	s_barrier
	s_add_i32 s34, s46, s92
	s_mov_b32 m0, s34
	ds_read_b128 v[160:163], v245 offset:49152
	ds_read_b128 v[164:167], v245 offset:50176
	ds_read_b128 v[182:185], v245 offset:51200
	ds_read_b128 v[186:189], v245 offset:52224
	ds_read_b128 v[190:193], v245 offset:53248
	ds_read_b128 v[194:197], v245 offset:54272
	ds_read_b128 v[198:201], v245 offset:55296
	ds_read_b128 v[202:205], v245 offset:56320
	global_load_lds_dwordx4 v174, s[94:95]
	s_add_i32 m0, s34, 0x2000
	s_add_u32 s30, s30, 0x40080
	s_addc_u32 s31, s31, 0
	s_add_i32 s34, s47, s92
	global_load_lds_dwordx4 v176, s[94:95]
	s_mov_b32 m0, s34
	s_nop 0
	global_load_lds_dwordx4 v174, s[30:31]
	s_add_i32 m0, s34, 0x2000
	s_nop 0
	global_load_lds_dwordx4 v176, s[30:31]
	s_mov_b32 m0, s8
	s_nop 0
	global_load_lds_dwordx4 v174, s[96:97]
	s_mov_b32 m0, s9
	s_nop 0
	global_load_lds_dwordx4 v176, s[96:97]
	s_waitcnt vmcnt(8)
	s_waitcnt lgkmcnt(0)
	s_barrier
	s_waitcnt lgkmcnt(0)
	v_mfma_f32_16x16x32_bf16 v[108:111], v[84:87], v[160:163], v[108:111]
	v_mfma_f32_16x16x32_bf16 v[28:31], v[96:99], v[160:163], v[28:31]
	v_mfma_f32_16x16x32_bf16 v[100:103], v[84:87], v[182:185], v[100:103]
	v_mfma_f32_16x16x32_bf16 v[20:23], v[96:99], v[182:185], v[20:23]
	v_mfma_f32_16x16x32_bf16 v[92:95], v[84:87], v[190:193], v[92:95]
	v_mfma_f32_16x16x32_bf16 v[12:15], v[96:99], v[190:193], v[12:15]
	v_mfma_f32_16x16x32_bf16 v[44:47], v[84:87], v[198:201], v[44:47]
	v_mfma_f32_16x16x32_bf16 v[4:7], v[96:99], v[198:201], v[4:7]
	v_mfma_f32_16x16x32_bf16 v[108:111], v[88:91], v[164:167], v[108:111]
	v_mfma_f32_16x16x32_bf16 v[28:31], v[104:107], v[164:167], v[28:31]
	v_mfma_f32_16x16x32_bf16 v[100:103], v[88:91], v[186:189], v[100:103]
	v_mfma_f32_16x16x32_bf16 v[20:23], v[104:107], v[186:189], v[20:23]
	v_mfma_f32_16x16x32_bf16 v[92:95], v[88:91], v[194:197], v[92:95]
	v_mfma_f32_16x16x32_bf16 v[12:15], v[104:107], v[194:197], v[12:15]
	v_mfma_f32_16x16x32_bf16 v[84:87], v[88:91], v[202:205], v[44:47]
	v_mfma_f32_16x16x32_bf16 v[4:7], v[104:107], v[202:205], v[4:7]
	v_mfma_f32_16x16x32_bf16 v[44:47], v[124:127], v[160:163], v[48:51]
	v_mfma_f32_16x16x32_bf16 v[104:107], v[128:131], v[164:167], v[44:47]
	v_mfma_f32_16x16x32_bf16 v[44:47], v[124:127], v[182:185], v[52:55]
	v_mfma_f32_16x16x32_bf16 v[96:99], v[128:131], v[186:189], v[44:47]
	v_mfma_f32_16x16x32_bf16 v[44:47], v[124:127], v[190:193], v[56:59]
	v_mfma_f32_16x16x32_bf16 v[24:27], v[132:135], v[160:163], v[24:27]
	v_mfma_f32_16x16x32_bf16 v[16:19], v[132:135], v[182:185], v[16:19]
	v_mfma_f32_16x16x32_bf16 v[88:91], v[128:131], v[194:197], v[44:47]
	v_mfma_f32_16x16x32_bf16 v[8:11], v[132:135], v[190:193], v[8:11]
	v_mfma_f32_16x16x32_bf16 v[44:47], v[124:127], v[198:201], v[80:83]
	v_mfma_f32_16x16x32_bf16 v[0:3], v[132:135], v[198:201], v[0:3]
	v_mfma_f32_16x16x32_bf16 v[24:27], v[136:139], v[164:167], v[24:27]
	v_mfma_f32_16x16x32_bf16 v[16:19], v[136:139], v[186:189], v[16:19]
	v_mfma_f32_16x16x32_bf16 v[8:11], v[136:139], v[194:197], v[8:11]
	v_mfma_f32_16x16x32_bf16 v[80:83], v[128:131], v[202:205], v[44:47]
	v_mfma_f32_16x16x32_bf16 v[0:3], v[136:139], v[202:205], v[0:3]
	s_barrier
	s_add_i32 s45, s45, 2
	s_add_u32 s0, s0, 0x100
	s_addc_u32 s1, s1, 0
	s_add_u32 s43, s43, 0x100
	s_addc_u32 s44, s44, 0
	s_cmp_gt_u32 s45, 13
	s_cbranch_scc0 .LBB0_826
	s_and_b64 vcc, exec, s[18:19]
	s_cbranch_vccz .LBB0_829
	s_barrier

; #define PG8_STAGE(bufoff, gbase, voff) do { _Pragma("unroll") for (int _i = 0; _i < 2; ++_i) \
;         __builtin_amdgcn_global_load_lds((const unsigned*)((const char*)(gbase) + (voff)[_i]), (LAS unsigned*)(lds + (bufoff) + ldsw + _i * 8192), 16, 0, 0); } while (0)
; #define PG8_LDA(dst, b, h) do { _Pragma("unroll") for (int m = 0; m < 4; ++m) _Pragma("unroll") for (int k = 0; k < 2; ++k) dst[m][k] = *(const LAS bf16x8*)(lds + PG8_SA(b, h) + aoff + m * 2048 + k * 1024); } while (0)
; #define PG8_LDB(dst, b, h) do { _Pragma("unroll") for (int n = 0; n < 2; ++n) _Pragma("unroll") for (int k = 0; k < 2; ++k) dst[n][k] = *(const LAS bf16x8*)(lds + PG8_SB(b, h) + boff + n * 2048 + k * 1024); } while (0)
; #define PG8_MMA(ai, bj, At, Bt) do { __builtin_amdgcn_s_setprio(1); _Pragma("unroll") for (int m = 0; m < 4; ++m) _Pragma("unroll") for (int n = 0; n < 2; ++n) _Pragma("unroll") for (int k = 0; k < 2; ++k) \
;         acc[ai][bj][m][n] = __builtin_amdgcn_mfma_f32_16x16x32_bf16(Bt[n][k], At[m][k], acc[ai][bj][m][n], 0, 0, 0); __builtin_amdgcn_s_setprio(0); } while (0)
; #define PG8_WAIT_V(n) asm volatile("s_waitcnt vmcnt(" #n ")" ::: "memory")
; #define PG8_WAIT_L(n) asm volatile("s_waitcnt lgkmcnt(" #n ")" ::: "memory")
; #define PG8_BAR __builtin_amdgcn_s_barrier()
; #define PG8_SCHED __builtin_amdgcn_sched_barrier(0)
; template <class Epi, class Sched, bool ALIGN_EPI>
; DI void gemm_phase(LAS unsigned char* lds, const Gemm g, const Sched& S, const Epi& E) {
;     ...
;             const bool last = (t == nt - 2);
;             const char* a1 = cA + (size_t)(t + 1) * kstep;
;             const char* a2 = last ? nA : cA + (size_t)(t + 2) * kstep; const char* b2 = last ? nB : cB + (size_t)(t + 2) * kstep;
;             const char* a3 = a2 + kstep; const char* b3 = b2 + kstep;
;             PG8_LDB(B0, 0, 0); PG8_LDB(B1, 0, 1); PG8_SCHED; PG8_LDA(At, 0, 0); PG8_STAGE(PG8_SA(1, 1), a1 + hstep, voffA);
;             PG8_WAIT_V(8); PG8_WAIT_L(0); PG8_BAR; PG8_MMA(0, 0, At, B0); PG8_MMA(0, 1, At, B1); PG8_BAR; PG8_SCHED;
;             PG8_LDA(At, 0, 1); PG8_STAGE(PG8_SB(0, 0), b2, voffA); PG8_STAGE(PG8_SB(0, 1), b2 + hstep, voffA); PG8_STAGE(PG8_SA(0, 0), a2, voffA);
;             PG8_WAIT_V(8); PG8_WAIT_L(0); PG8_BAR; PG8_MMA(1, 0, At, B0); PG8_MMA(1, 1, At, B1); PG8_BAR; PG8_SCHED;
.LBB0_957:
	s_add_u32 s16, s0, 0xfffc0080
	s_addc_u32 s17, s1, -1
	s_add_i32 s43, 0, 0x10000
	s_cmp_eq_u32 s42, 12
	s_cselect_b32 s19, s5, s17
	s_cselect_b32 s18, s34, s16
	s_cselect_b32 s17, s15, s37
	s_cselect_b32 s16, s35, s36
	s_add_i32 s50, 0, 0x14000
	v_add_u32_e32 v144, s43, v133
	v_add_u32_e32 v160, s50, v133
	ds_read_b128 v[128:131], v144
	ds_read_b128 v[136:139], v144 offset:1024
	ds_read_b128 v[140:143], v144 offset:2048
	ds_read_b128 v[144:147], v144 offset:3072
	ds_read_b128 v[148:151], v160
	ds_read_b128 v[152:155], v160 offset:1024
	ds_read_b128 v[156:159], v160 offset:2048
	ds_read_b128 v[160:163], v160 offset:3072
	s_add_i32 m0, s22, 0xc000
	ds_read_b128 v[164:167], v135
	ds_read_b128 v[182:185], v135 offset:1024
	ds_read_b128 v[186:189], v135 offset:2048
	ds_read_b128 v[190:193], v135 offset:3072
	ds_read_b128 v[194:197], v135 offset:4096
	ds_read_b128 v[198:201], v135 offset:5120
	ds_read_b128 v[202:205], v135 offset:6144
	ds_read_b128 v[206:209], v135 offset:7168
	global_load_lds_dwordx4 v178, s[0:1]
	s_add_i32 m0, s22, 0xe000
	s_nop 0
	global_load_lds_dwordx4 v180, s[0:1]
	s_waitcnt vmcnt(8)
	s_waitcnt lgkmcnt(0)
	s_barrier
	s_waitcnt lgkmcnt(0)
	v_mfma_f32_16x16x32_bf16 v[124:127], v[128:131], v[164:167], v[124:127]
	v_mfma_f32_16x16x32_bf16 v[120:123], v[140:143], v[164:167], v[120:123]
	v_mfma_f32_16x16x32_bf16 v[108:111], v[128:131], v[186:189], v[108:111]
	v_mfma_f32_16x16x32_bf16 v[104:107], v[140:143], v[186:189], v[104:107]
	v_mfma_f32_16x16x32_bf16 v[92:95], v[128:131], v[194:197], v[92:95]
	v_mfma_f32_16x16x32_bf16 v[88:91], v[140:143], v[194:197], v[88:91]
	v_mfma_f32_16x16x32_bf16 v[76:79], v[128:131], v[202:205], v[76:79]
	v_mfma_f32_16x16x32_bf16 v[72:75], v[140:143], v[202:205], v[72:75]
	v_mfma_f32_16x16x32_bf16 v[124:127], v[136:139], v[182:185], v[124:127]
	v_mfma_f32_16x16x32_bf16 v[120:123], v[144:147], v[182:185], v[120:123]
	v_mfma_f32_16x16x32_bf16 v[108:111], v[136:139], v[190:193], v[108:111]
	v_mfma_f32_16x16x32_bf16 v[104:107], v[144:147], v[190:193], v[104:107]
	v_mfma_f32_16x16x32_bf16 v[92:95], v[136:139], v[198:201], v[92:95]
	v_mfma_f32_16x16x32_bf16 v[88:91], v[144:147], v[198:201], v[88:91]
	v_mfma_f32_16x16x32_bf16 v[76:79], v[136:139], v[206:209], v[76:79]
	v_mfma_f32_16x16x32_bf16 v[72:75], v[144:147], v[206:209], v[72:75]
	v_mfma_f32_16x16x32_bf16 v[116:119], v[148:151], v[164:167], v[116:119]
	v_mfma_f32_16x16x32_bf16 v[112:115], v[156:159], v[164:167], v[112:115]
	v_mfma_f32_16x16x32_bf16 v[100:103], v[148:151], v[186:189], v[100:103]
	v_mfma_f32_16x16x32_bf16 v[96:99], v[156:159], v[186:189], v[96:99]
	v_mfma_f32_16x16x32_bf16 v[84:87], v[148:151], v[194:197], v[84:87]
	v_mfma_f32_16x16x32_bf16 v[80:83], v[156:159], v[194:197], v[80:83]
	v_mfma_f32_16x16x32_bf16 v[68:71], v[148:151], v[202:205], v[68:71]
	v_mfma_f32_16x16x32_bf16 v[64:67], v[156:159], v[202:205], v[64:67]
	v_mfma_f32_16x16x32_bf16 v[116:119], v[152:155], v[182:185], v[116:119]
	v_mfma_f32_16x16x32_bf16 v[112:115], v[160:163], v[182:185], v[112:115]
	v_mfma_f32_16x16x32_bf16 v[100:103], v[152:155], v[190:193], v[100:103]
	v_mfma_f32_16x16x32_bf16 v[96:99], v[160:163], v[190:193], v[96:99]
	v_mfma_f32_16x16x32_bf16 v[84:87], v[152:155], v[198:201], v[84:87]
	v_mfma_f32_16x16x32_bf16 v[80:83], v[160:163], v[198:201], v[80:83]
	v_mfma_f32_16x16x32_bf16 v[68:71], v[152:155], v[206:209], v[68:71]
	v_mfma_f32_16x16x32_bf16 v[64:67], v[160:163], v[206:209], v[64:67]
	s_barrier
	s_add_i32 s43, s43, s20
	s_add_u32 s94, s16, s2
	s_addc_u32 s95, s17, s3
	s_add_u32 s96, s18, s2
	s_addc_u32 s97, s19, s3
	s_mov_b32 m0, s43
	ds_read_b128 v[164:167], v135 offset:16384
	ds_read_b128 v[182:185], v135 offset:17408
	ds_read_b128 v[186:189], v135 offset:18432
	ds_read_b128 v[190:193], v135 offset:19456
	ds_read_b128 v[194:197], v135 offset:20480
	ds_read_b128 v[198:201], v135 offset:21504
	ds_read_b128 v[202:205], v135 offset:22528
	ds_read_b128 v[206:209], v135 offset:23552
	global_load_lds_dwordx4 v174, s[16:17]
	s_add_i32 m0, s43, 0x2000
	s_add_u32 s48, s16, 0x40000
	s_addc_u32 s49, s17, 0
	s_add_i32 s43, s50, s20
	global_load_lds_dwordx4 v176, s[16:17]
	s_mov_b32 m0, s43
	s_nop 0
	global_load_lds_dwordx4 v174, s[48:49]
	s_add_i32 m0, s43, 0x2000
	s_nop 0
	global_load_lds_dwordx4 v176, s[48:49]
	s_mov_b32 m0, s22
	s_nop 0
	global_load_lds_dwordx4 v174, s[18:19]
	s_mov_b32 m0, s23
	s_nop 0
	global_load_lds_dwordx4 v176, s[18:19]
	s_waitcnt vmcnt(8)
	s_waitcnt lgkmcnt(0)
	s_barrier
	s_waitcnt lgkmcnt(0)
	v_mfma_f32_16x16x32_bf16 v[60:63], v[128:131], v[164:167], v[60:63]
	v_mfma_f32_16x16x32_bf16 v[56:59], v[140:143], v[164:167], v[56:59]
	v_mfma_f32_16x16x32_bf16 v[44:47], v[128:131], v[186:189], v[44:47]
	v_mfma_f32_16x16x32_bf16 v[40:43], v[140:143], v[186:189], v[40:43]
	v_mfma_f32_16x16x32_bf16 v[28:31], v[128:131], v[194:197], v[28:31]
	v_mfma_f32_16x16x32_bf16 v[24:27], v[140:143], v[194:197], v[24:27]
	v_mfma_f32_16x16x32_bf16 v[12:15], v[128:131], v[202:205], v[12:15]
	v_mfma_f32_16x16x32_bf16 v[8:11], v[140:143], v[202:205], v[8:11]
	v_mfma_f32_16x16x32_bf16 v[60:63], v[136:139], v[182:185], v[60:63]
	v_mfma_f32_16x16x32_bf16 v[56:59], v[144:147], v[182:185], v[56:59]
	v_mfma_f32_16x16x32_bf16 v[44:47], v[136:139], v[190:193], v[44:47]
	v_mfma_f32_16x16x32_bf16 v[40:43], v[144:147], v[190:193], v[40:43]
	v_mfma_f32_16x16x32_bf16 v[28:31], v[136:139], v[198:201], v[28:31]
	v_mfma_f32_16x16x32_bf16 v[24:27], v[144:147], v[198:201], v[24:27]
	v_mfma_f32_16x16x32_bf16 v[12:15], v[136:139], v[206:209], v[12:15]
	v_mfma_f32_16x16x32_bf16 v[8:11], v[144:147], v[206:209], v[8:11]
	v_mfma_f32_16x16x32_bf16 v[52:55], v[148:151], v[164:167], v[52:55]
	v_mfma_f32_16x16x32_bf16 v[48:51], v[156:159], v[164:167], v[48:51]
	v_mfma_f32_16x16x32_bf16 v[36:39], v[148:151], v[186:189], v[36:39]
	v_mfma_f32_16x16x32_bf16 v[32:35], v[156:159], v[186:189], v[32:35]
	v_mfma_f32_16x16x32_bf16 v[20:23], v[148:151], v[194:197], v[20:23]
	v_mfma_f32_16x16x32_bf16 v[16:19], v[156:159], v[194:197], v[16:19]
	v_mfma_f32_16x16x32_bf16 v[4:7], v[148:151], v[202:205], v[4:7]
	v_mfma_f32_16x16x32_bf16 v[0:3], v[156:159], v[202:205], v[0:3]
	v_mfma_f32_16x16x32_bf16 v[52:55], v[152:155], v[182:185], v[52:55]
	v_mfma_f32_16x16x32_bf16 v[48:51], v[160:163], v[182:185], v[48:51]
	v_mfma_f32_16x16x32_bf16 v[36:39], v[152:155], v[190:193], v[36:39]
	v_mfma_f32_16x16x32_bf16 v[32:35], v[160:163], v[190:193], v[32:35]
	v_mfma_f32_16x16x32_bf16 v[20:23], v[152:155], v[198:201], v[20:23]
	v_mfma_f32_16x16x32_bf16 v[16:19], v[160:163], v[198:201], v[16:19]
	v_mfma_f32_16x16x32_bf16 v[4:7], v[152:155], v[206:209], v[4:7]
	v_mfma_f32_16x16x32_bf16 v[0:3], v[160:163], v[206:209], v[0:3]
	s_barrier
; #define PG8_STAGE(bufoff, gbase, voff) do { _Pragma("unroll") for (int _i = 0; _i < 2; ++_i) \
;         __builtin_amdgcn_global_load_lds((const unsigned*)((const char*)(gbase) + (voff)[_i]), (LAS unsigned*)(lds + (bufoff) + ldsw + _i * 8192), 16, 0, 0); } while (0)
; #define PG8_LDA(dst, b, h) do { _Pragma("unroll") for (int m = 0; m < 4; ++m) _Pragma("unroll") for (int k = 0; k < 2; ++k) dst[m][k] = *(const LAS bf16x8*)(lds + PG8_SA(b, h) + aoff + m * 2048 + k * 1024); } while (0)
; #define PG8_LDB(dst, b, h) do { _Pragma("unroll") for (int n = 0; n < 2; ++n) _Pragma("unroll") for (int k = 0; k < 2; ++k) dst[n][k] = *(const LAS bf16x8*)(lds + PG8_SB(b, h) + boff + n * 2048 + k * 1024); } while (0)
; #define PG8_MMA(ai, bj, At, Bt) do { __builtin_amdgcn_s_setprio(1); _Pragma("unroll") for (int m = 0; m < 4; ++m) _Pragma("unroll") for (int n = 0; n < 2; ++n) _Pragma("unroll") for (int k = 0; k < 2; ++k) \
;         acc[ai][bj][m][n] = __builtin_amdgcn_mfma_f32_16x16x32_bf16(Bt[n][k], At[m][k], acc[ai][bj][m][n], 0, 0, 0); __builtin_amdgcn_s_setprio(0); } while (0)
; #define PG8_WAIT_V(n) asm volatile("s_waitcnt vmcnt(" #n ")" ::: "memory")
; #define PG8_WAIT_L(n) asm volatile("s_waitcnt lgkmcnt(" #n ")" ::: "memory")
; #define PG8_BAR __builtin_amdgcn_s_barrier()
; #define PG8_SCHED __builtin_amdgcn_sched_barrier(0)
; template <class Epi, class Sched, bool ALIGN_EPI>
; DI void gemm_phase(LAS unsigned char* lds, const Gemm g, const Sched& S, const Epi& E) {
;     ...
;             PG8_LDB(B0, 1, 0); PG8_LDB(B1, 1, 1); PG8_SCHED; PG8_LDA(At, 1, 0); PG8_STAGE(PG8_SA(0, 1), a2 + hstep, voffA);
;             PG8_WAIT_V(8); PG8_WAIT_L(0); PG8_BAR; PG8_MMA(0, 0, At, B0); PG8_MMA(0, 1, At, B1); PG8_BAR; PG8_SCHED;
;             PG8_LDA(At, 1, 1); PG8_STAGE(PG8_SB(1, 0), b3, voffA); PG8_STAGE(PG8_SB(1, 1), b3 + hstep, voffA); PG8_STAGE(PG8_SA(1, 0), a3, voffA);
;             PG8_WAIT_V(8); PG8_WAIT_L(0); PG8_BAR; PG8_MMA(1, 0, At, B0); PG8_MMA(1, 1, At, B1); PG8_BAR; PG8_SCHED;
;         }
	s_add_i32 s43, 0, 0x18000
	s_add_i32 s48, 0, 0x1c000
	v_add_u32_e32 v144, s43, v133
	v_add_u32_e32 v160, s48, v133
	ds_read_b128 v[128:131], v144
	ds_read_b128 v[136:139], v144 offset:1024
	ds_read_b128 v[140:143], v144 offset:2048
	ds_read_b128 v[144:147], v144 offset:3072
	ds_read_b128 v[148:151], v160
	ds_read_b128 v[152:155], v160 offset:1024
	ds_read_b128 v[156:159], v160 offset:2048
	ds_read_b128 v[160:163], v160 offset:3072
	s_add_u32 s18, s18, 0x40000
	s_addc_u32 s19, s19, 0
	s_mov_b32 m0, s24
	ds_read_b128 v[164:167], v135 offset:32768
	ds_read_b128 v[182:185], v135 offset:33792
	ds_read_b128 v[186:189], v135 offset:34816
	ds_read_b128 v[190:193], v135 offset:35840
	ds_read_b128 v[194:197], v135 offset:36864
	ds_read_b128 v[198:201], v135 offset:37888
	ds_read_b128 v[202:205], v135 offset:38912
	ds_read_b128 v[206:209], v135 offset:39936
	global_load_lds_dwordx4 v174, s[18:19]
	s_mov_b32 m0, s25
	s_nop 0
	global_load_lds_dwordx4 v176, s[18:19]
	s_waitcnt vmcnt(8)
	s_waitcnt lgkmcnt(0)
	s_barrier
	s_waitcnt lgkmcnt(0)
	v_mfma_f32_16x16x32_bf16 v[124:127], v[128:131], v[164:167], v[124:127]
	v_mfma_f32_16x16x32_bf16 v[120:123], v[140:143], v[164:167], v[120:123]
	v_mfma_f32_16x16x32_bf16 v[108:111], v[128:131], v[186:189], v[108:111]
	v_mfma_f32_16x16x32_bf16 v[104:107], v[140:143], v[186:189], v[104:107]
	v_mfma_f32_16x16x32_bf16 v[92:95], v[128:131], v[194:197], v[92:95]
	v_mfma_f32_16x16x32_bf16 v[88:91], v[140:143], v[194:197], v[88:91]
	v_mfma_f32_16x16x32_bf16 v[76:79], v[128:131], v[202:205], v[76:79]
	v_mfma_f32_16x16x32_bf16 v[72:75], v[140:143], v[202:205], v[72:75]
	v_mfma_f32_16x16x32_bf16 v[124:127], v[136:139], v[182:185], v[124:127]
	v_mfma_f32_16x16x32_bf16 v[120:123], v[144:147], v[182:185], v[120:123]
	v_mfma_f32_16x16x32_bf16 v[108:111], v[136:139], v[190:193], v[108:111]
	v_mfma_f32_16x16x32_bf16 v[104:107], v[144:147], v[190:193], v[104:107]
	v_mfma_f32_16x16x32_bf16 v[92:95], v[136:139], v[198:201], v[92:95]
	v_mfma_f32_16x16x32_bf16 v[88:91], v[144:147], v[198:201], v[88:91]
	v_mfma_f32_16x16x32_bf16 v[76:79], v[136:139], v[206:209], v[76:79]
	v_mfma_f32_16x16x32_bf16 v[72:75], v[144:147], v[206:209], v[72:75]
	v_mfma_f32_16x16x32_bf16 v[116:119], v[148:151], v[164:167], v[116:119]
	v_mfma_f32_16x16x32_bf16 v[112:115], v[156:159], v[164:167], v[112:115]
	v_mfma_f32_16x16x32_bf16 v[100:103], v[148:151], v[186:189], v[100:103]
	v_mfma_f32_16x16x32_bf16 v[96:99], v[156:159], v[186:189], v[96:99]
	v_mfma_f32_16x16x32_bf16 v[84:87], v[148:151], v[194:197], v[84:87]
	v_mfma_f32_16x16x32_bf16 v[80:83], v[156:159], v[194:197], v[80:83]
	v_mfma_f32_16x16x32_bf16 v[68:71], v[148:151], v[202:205], v[68:71]
	v_mfma_f32_16x16x32_bf16 v[64:67], v[156:159], v[202:205], v[64:67]
	v_mfma_f32_16x16x32_bf16 v[116:119], v[152:155], v[182:185], v[116:119]
	v_mfma_f32_16x16x32_bf16 v[112:115], v[160:163], v[182:185], v[112:115]
	v_mfma_f32_16x16x32_bf16 v[100:103], v[152:155], v[190:193], v[100:103]
	v_mfma_f32_16x16x32_bf16 v[96:99], v[160:163], v[190:193], v[96:99]
	v_mfma_f32_16x16x32_bf16 v[84:87], v[152:155], v[198:201], v[84:87]
	v_mfma_f32_16x16x32_bf16 v[80:83], v[160:163], v[198:201], v[80:83]
	v_mfma_f32_16x16x32_bf16 v[68:71], v[152:155], v[206:209], v[68:71]
	v_mfma_f32_16x16x32_bf16 v[64:67], v[160:163], v[206:209], v[64:67]
	s_barrier
	s_add_i32 s18, s43, s20
	s_mov_b32 m0, s18
	ds_read_b128 v[164:167], v135 offset:49152
	ds_read_b128 v[182:185], v135 offset:50176
	ds_read_b128 v[186:189], v135 offset:51200
	ds_read_b128 v[190:193], v135 offset:52224
	ds_read_b128 v[194:197], v135 offset:53248
	ds_read_b128 v[198:201], v135 offset:54272
	ds_read_b128 v[202:205], v135 offset:55296
	ds_read_b128 v[206:209], v135 offset:56320
	global_load_lds_dwordx4 v174, s[94:95]
	s_add_i32 m0, s18, 0x2000
	s_add_u32 s16, s16, 0x40080
	s_addc_u32 s17, s17, 0
	s_add_i32 s18, s48, s20
	global_load_lds_dwordx4 v176, s[94:95]
	s_mov_b32 m0, s18
	s_nop 0
	global_load_lds_dwordx4 v174, s[16:17]
	s_add_i32 m0, s18, 0x2000
	s_nop 0
	global_load_lds_dwordx4 v176, s[16:17]
	s_mov_b32 m0, s26
	s_nop 0
	global_load_lds_dwordx4 v174, s[96:97]
	s_mov_b32 m0, s27
	s_nop 0
	global_load_lds_dwordx4 v176, s[96:97]
	s_waitcnt vmcnt(8)
	s_waitcnt lgkmcnt(0)
	s_barrier
	s_waitcnt lgkmcnt(0)
	v_mfma_f32_16x16x32_bf16 v[60:63], v[128:131], v[164:167], v[60:63]
	v_mfma_f32_16x16x32_bf16 v[56:59], v[140:143], v[164:167], v[56:59]
	v_mfma_f32_16x16x32_bf16 v[44:47], v[128:131], v[186:189], v[44:47]
	v_mfma_f32_16x16x32_bf16 v[40:43], v[140:143], v[186:189], v[40:43]
	v_mfma_f32_16x16x32_bf16 v[28:31], v[128:131], v[194:197], v[28:31]
	v_mfma_f32_16x16x32_bf16 v[24:27], v[140:143], v[194:197], v[24:27]
	v_mfma_f32_16x16x32_bf16 v[12:15], v[128:131], v[202:205], v[12:15]
	v_mfma_f32_16x16x32_bf16 v[8:11], v[140:143], v[202:205], v[8:11]
	v_mfma_f32_16x16x32_bf16 v[60:63], v[136:139], v[182:185], v[60:63]
	v_mfma_f32_16x16x32_bf16 v[56:59], v[144:147], v[182:185], v[56:59]
	v_mfma_f32_16x16x32_bf16 v[44:47], v[136:139], v[190:193], v[44:47]
	v_mfma_f32_16x16x32_bf16 v[40:43], v[144:147], v[190:193], v[40:43]
	v_mfma_f32_16x16x32_bf16 v[28:31], v[136:139], v[198:201], v[28:31]
	v_mfma_f32_16x16x32_bf16 v[24:27], v[144:147], v[198:201], v[24:27]
	v_mfma_f32_16x16x32_bf16 v[12:15], v[136:139], v[206:209], v[12:15]
	v_mfma_f32_16x16x32_bf16 v[8:11], v[144:147], v[206:209], v[8:11]
	v_mfma_f32_16x16x32_bf16 v[52:55], v[148:151], v[164:167], v[52:55]
	v_mfma_f32_16x16x32_bf16 v[48:51], v[156:159], v[164:167], v[48:51]
	v_mfma_f32_16x16x32_bf16 v[36:39], v[148:151], v[186:189], v[36:39]
	v_mfma_f32_16x16x32_bf16 v[32:35], v[156:159], v[186:189], v[32:35]
	v_mfma_f32_16x16x32_bf16 v[20:23], v[148:151], v[194:197], v[20:23]
	v_mfma_f32_16x16x32_bf16 v[16:19], v[156:159], v[194:197], v[16:19]
	v_mfma_f32_16x16x32_bf16 v[4:7], v[148:151], v[202:205], v[4:7]
	v_mfma_f32_16x16x32_bf16 v[0:3], v[156:159], v[202:205], v[0:3]
	v_mfma_f32_16x16x32_bf16 v[52:55], v[152:155], v[182:185], v[52:55]
	v_mfma_f32_16x16x32_bf16 v[48:51], v[160:163], v[182:185], v[48:51]
	v_mfma_f32_16x16x32_bf16 v[36:39], v[152:155], v[190:193], v[36:39]
	v_mfma_f32_16x16x32_bf16 v[32:35], v[160:163], v[190:193], v[32:35]
	v_mfma_f32_16x16x32_bf16 v[20:23], v[152:155], v[198:201], v[20:23]
	v_mfma_f32_16x16x32_bf16 v[16:19], v[160:163], v[198:201], v[16:19]
	v_mfma_f32_16x16x32_bf16 v[4:7], v[152:155], v[206:209], v[4:7]
	v_mfma_f32_16x16x32_bf16 v[0:3], v[160:163], v[206:209], v[0:3]
	s_barrier
	s_add_i32 s42, s42, 2
	s_add_u32 s0, s0, 0x100
	s_addc_u32 s1, s1, 0
	s_add_u32 s36, s36, 0x100
	s_addc_u32 s37, s37, 0
	s_cmp_gt_u32 s42, 13
	s_cbranch_scc0 .LBB0_957
	s_and_b64 vcc, exec, s[12:13]
	s_cbranch_vccz .LBB0_960
	s_barrier
